# fused P6/P9 epilogues: second half of the f32 U stores issued after the partial-statistics loads, counted vmcnt waits so the combine does not wait for the store drain
# speedup vs baseline: 1.0009x; 1.0009x over previous
.LBB0_1017:
	v_lshlrev_b32_e32 v130, 3, v152
	v_and_b32_e32 v130, 0x78, v130
	v_ashrrev_i32_e32 v151, 4, v152
	v_lshrrev_b32_e32 v132, 1, v152
	v_and_b32_e32 v191, 0x60, v132
	v_or_b32_e32 v132, 4, v130
	v_lshlrev_b32_e32 v133, 2, v151
	v_bitop3_b32 v134, v133, v130, 48 bitop3:0x6c
	v_bitop3_b32 v133, v133, v132, 48 bitop3:0x6c
	v_lshlrev_b32_e32 v135, 9, v151
	v_lshlrev_b32_e32 v133, 2, v133
	v_add_u32_e32 v150, 32, v151
	v_lshlrev_b32_e32 v134, 2, v134
	v_add3_u32 v147, s77, v133, v135
	v_lshlrev_b32_e32 v133, 2, v150
	v_add3_u32 v146, s77, v134, v135
	v_bitop3_b32 v134, v133, v130, 48 bitop3:0x6c
	v_bitop3_b32 v133, v133, v132, 48 bitop3:0x6c
	v_lshlrev_b32_e32 v135, 9, v150
	v_lshlrev_b32_e32 v133, 2, v133
	v_add_u32_e32 v149, 64, v151
	v_lshlrev_b32_e32 v134, 2, v134
	v_add3_u32 v144, s77, v133, v135
	v_lshlrev_b32_e32 v133, 2, v149
	v_add3_u32 v145, s77, v134, v135
	v_bitop3_b32 v134, v133, v130, 48 bitop3:0x6c
	v_bitop3_b32 v133, v133, v132, 48 bitop3:0x6c
	v_lshlrev_b32_e32 v135, 9, v149
	v_lshlrev_b32_e32 v133, 2, v133
	v_add_u32_e32 v148, 0x60, v151
	v_lshlrev_b32_e32 v134, 2, v134
	v_add3_u32 v142, s77, v133, v135
	v_lshlrev_b32_e32 v133, 2, v148
	v_add3_u32 v143, s77, v134, v135
	v_bitop3_b32 v134, v133, v130, 48 bitop3:0x6c
	v_lshlrev_b32_e32 v134, 2, v134
	v_lshlrev_b32_e32 v135, 9, v148
	v_bitop3_b32 v132, v133, v132, 48 bitop3:0x6c
	s_lshl_b64 s[44:45], s[36:37], 2
	v_add3_u32 v141, s77, v134, v135
	v_lshlrev_b32_e32 v132, 2, v132
	v_add_u32_e32 v134, s38, v151
	s_add_u32 s44, s64, s44
	v_add3_u32 v140, s77, v132, v135
	v_bfe_u32 v190, v152, 4, 2
	v_and_b32_e32 v153, 15, v152
	v_lshlrev_b32_e32 v193, 4, v190
	v_lshlrev_b32_e32 v152, 7, v152
	v_or_b32_e32 v192, v191, v153
	v_bitop3_b32 v153, v191, v193, v153 bitop3:0x36
	v_and_b32_e32 v152, 0xffff8000, v152
	v_lshlrev_b32_e32 v153, 2, v153
	v_lshl_or_b32 v190, v190, 11, v152
	v_add3_u32 v152, s77, v153, v190
	v_bitop3_b32 v149, v192, v193, 16 bitop3:0x36
	v_lshlrev_b32_e32 v149, 2, v149
	v_add3_u32 v149, s77, v149, v190
	v_lshrrev_b32_e32 v227, 4, v0
	v_add_u32_e32 v130, s38, v227
	v_lshlrev_b32_e32 v227, 3, v227
	v_and_b32_e32 v226, 15, v0
	v_lshlrev_b32_e32 v226, 5, v226
	s_lshl_b32 s0, s36, 2
	v_add_u32_e32 v226, s0, v226
	v_mov_b32_e32 v229, 0
	v_mov_b32_e32 v228, v130
	v_lshlrev_b64 v[228:229], 12, v[228:229]
	v_mov_b32_e32 v230, v226
	v_mov_b32_e32 v231, 0
	v_lshl_add_u64 v[228:229], v[228:229], 0, v[230:231]
	v_lshl_add_u64 v[230:231], s[64:65], 0, v[228:229]
	s_mov_b32 s44, 0x20000
	s_mov_b32 s45, 0
	s_mov_b32 s71, 0
	s_nop 1
	s_mov_b32 s70, 0x0
	v_lshl_add_u64 v[150:151], v[230:231], 0, s[70:71]
	v_lshl_add_u64 v[220:221], v[150:151], 0, s[44:45]
	v_lshl_add_u64 v[222:223], v[220:221], 0, s[44:45]
	v_lshl_add_u64 v[224:225], v[222:223], 0, s[44:45]
	global_load_dwordx4 v[186:189], v[150:151], off
	global_load_dwordx4 v[190:193], v[150:151], off offset:16
	global_load_dwordx4 v[194:197], v[220:221], off
	global_load_dwordx4 v[198:201], v[220:221], off offset:16
	global_load_dwordx4 v[202:205], v[222:223], off
	global_load_dwordx4 v[206:209], v[222:223], off offset:16
	global_load_dwordx4 v[210:213], v[224:225], off
	global_load_dwordx4 v[214:217], v[224:225], off offset:16
	ds_write2st64_b32 v152, v126, v127 offset1:2
	ds_write2st64_b32 v152, v128, v129 offset0:4 offset1:6
	ds_write2st64_b32 v149, v98, v99 offset1:2
	ds_write2st64_b32 v149, v100, v101 offset0:4 offset1:6
	ds_write2st64_b32 v152, v102, v103 offset0:32 offset1:34
	ds_write2st64_b32 v152, v104, v105 offset0:36 offset1:38
	ds_write2st64_b32 v149, v106, v107 offset0:32 offset1:34
	ds_write2st64_b32 v149, v108, v109 offset0:36 offset1:38
	ds_write2st64_b32 v152, v110, v111 offset0:64 offset1:66
	ds_write2st64_b32 v152, v112, v113 offset0:68 offset1:70
	ds_write2st64_b32 v149, v114, v115 offset0:64 offset1:66
	ds_write2st64_b32 v149, v116, v117 offset0:68 offset1:70
	ds_write2st64_b32 v152, v118, v119 offset0:96 offset1:98
	ds_write2st64_b32 v152, v120, v121 offset0:100 offset1:102
	ds_write2st64_b32 v149, v122, v123 offset0:96 offset1:98
	ds_write2st64_b32 v149, v124, v125 offset0:100 offset1:102
	s_waitcnt lgkmcnt(0)
	s_barrier
	ds_read_b128 v[154:157], v146
	ds_read_b128 v[158:161], v147
	ds_read_b128 v[162:165], v145
	ds_read_b128 v[166:169], v144
	ds_read_b128 v[170:173], v143
	ds_read_b128 v[174:177], v142
	ds_read_b128 v[178:181], v141
	ds_read_b128 v[182:185], v140
	s_waitcnt vmcnt(0) lgkmcnt(0)
	s_barrier
	v_pk_fma_f32 v[98:99], v[186:187], s[30:31], v[154:155] op_sel_hi:[1,0,1]
	v_pk_fma_f32 v[100:101], v[188:189], s[30:31], v[156:157] op_sel_hi:[1,0,1]
	v_pk_fma_f32 v[102:103], v[190:191], s[30:31], v[158:159] op_sel_hi:[1,0,1]
	v_pk_fma_f32 v[104:105], v[192:193], s[30:31], v[160:161] op_sel_hi:[1,0,1]
	v_pk_fma_f32 v[106:107], v[194:195], s[30:31], v[162:163] op_sel_hi:[1,0,1]
	v_pk_fma_f32 v[108:109], v[196:197], s[30:31], v[164:165] op_sel_hi:[1,0,1]
	v_pk_fma_f32 v[110:111], v[198:199], s[30:31], v[166:167] op_sel_hi:[1,0,1]
	v_pk_fma_f32 v[112:113], v[200:201], s[30:31], v[168:169] op_sel_hi:[1,0,1]
	v_pk_fma_f32 v[114:115], v[202:203], s[30:31], v[170:171] op_sel_hi:[1,0,1]
	v_pk_fma_f32 v[116:117], v[204:205], s[30:31], v[172:173] op_sel_hi:[1,0,1]
	v_pk_fma_f32 v[118:119], v[206:207], s[30:31], v[174:175] op_sel_hi:[1,0,1]
	v_pk_fma_f32 v[120:121], v[208:209], s[30:31], v[176:177] op_sel_hi:[1,0,1]
	v_pk_fma_f32 v[122:123], v[210:211], s[30:31], v[178:179] op_sel_hi:[1,0,1]
	v_pk_fma_f32 v[124:125], v[212:213], s[30:31], v[180:181] op_sel_hi:[1,0,1]
	v_pk_fma_f32 v[126:127], v[214:215], s[30:31], v[182:183] op_sel_hi:[1,0,1]
	v_pk_fma_f32 v[128:129], v[216:217], s[30:31], v[184:185] op_sel_hi:[1,0,1]
	s_mov_b32 s70, 0x200
	v_lshl_add_u64 v[150:151], v[230:231], 0, s[70:71]
	v_lshl_add_u64 v[220:221], v[150:151], 0, s[44:45]
	v_lshl_add_u64 v[222:223], v[220:221], 0, s[44:45]
	v_lshl_add_u64 v[224:225], v[222:223], 0, s[44:45]
	global_load_dwordx4 v[186:189], v[150:151], off
	global_load_dwordx4 v[190:193], v[150:151], off offset:16
	global_load_dwordx4 v[194:197], v[220:221], off
	global_load_dwordx4 v[198:201], v[220:221], off offset:16
	global_load_dwordx4 v[202:205], v[222:223], off
	global_load_dwordx4 v[206:209], v[222:223], off offset:16
	global_load_dwordx4 v[210:213], v[224:225], off
	global_load_dwordx4 v[214:217], v[224:225], off offset:16
	ds_write2st64_b32 v152, v66, v67 offset1:2
	ds_write2st64_b32 v152, v68, v69 offset0:4 offset1:6
	ds_write2st64_b32 v149, v70, v71 offset1:2
	ds_write2st64_b32 v149, v72, v73 offset0:4 offset1:6
	ds_write2st64_b32 v152, v74, v75 offset0:32 offset1:34
	ds_write2st64_b32 v152, v76, v77 offset0:36 offset1:38
	ds_write2st64_b32 v149, v78, v79 offset0:32 offset1:34
	ds_write2st64_b32 v149, v80, v81 offset0:36 offset1:38
	ds_write2st64_b32 v152, v82, v83 offset0:64 offset1:66
	ds_write2st64_b32 v152, v84, v85 offset0:68 offset1:70
	ds_write2st64_b32 v149, v86, v87 offset0:64 offset1:66
	ds_write2st64_b32 v149, v88, v89 offset0:68 offset1:70
	ds_write2st64_b32 v152, v90, v91 offset0:96 offset1:98
	ds_write2st64_b32 v152, v92, v93 offset0:100 offset1:102
	ds_write2st64_b32 v149, v94, v95 offset0:96 offset1:98
	ds_write2st64_b32 v149, v96, v97 offset0:100 offset1:102
	s_waitcnt lgkmcnt(0)
	s_barrier
	ds_read_b128 v[154:157], v146
	ds_read_b128 v[158:161], v147
	ds_read_b128 v[162:165], v145
	ds_read_b128 v[166:169], v144
	ds_read_b128 v[170:173], v143
	ds_read_b128 v[174:177], v142
	ds_read_b128 v[178:181], v141
	ds_read_b128 v[182:185], v140
	s_waitcnt vmcnt(0) lgkmcnt(0)
	s_barrier
	v_pk_fma_f32 v[66:67], v[186:187], s[30:31], v[154:155] op_sel_hi:[1,0,1]
	v_pk_fma_f32 v[68:69], v[188:189], s[30:31], v[156:157] op_sel_hi:[1,0,1]
	v_pk_fma_f32 v[70:71], v[190:191], s[30:31], v[158:159] op_sel_hi:[1,0,1]
	v_pk_fma_f32 v[72:73], v[192:193], s[30:31], v[160:161] op_sel_hi:[1,0,1]
	v_pk_fma_f32 v[74:75], v[194:195], s[30:31], v[162:163] op_sel_hi:[1,0,1]
	v_pk_fma_f32 v[76:77], v[196:197], s[30:31], v[164:165] op_sel_hi:[1,0,1]
	v_pk_fma_f32 v[78:79], v[198:199], s[30:31], v[166:167] op_sel_hi:[1,0,1]
	v_pk_fma_f32 v[80:81], v[200:201], s[30:31], v[168:169] op_sel_hi:[1,0,1]
	v_pk_fma_f32 v[82:83], v[202:203], s[30:31], v[170:171] op_sel_hi:[1,0,1]
	v_pk_fma_f32 v[84:85], v[204:205], s[30:31], v[172:173] op_sel_hi:[1,0,1]
	v_pk_fma_f32 v[86:87], v[206:207], s[30:31], v[174:175] op_sel_hi:[1,0,1]
	v_pk_fma_f32 v[88:89], v[208:209], s[30:31], v[176:177] op_sel_hi:[1,0,1]
	v_pk_fma_f32 v[90:91], v[210:211], s[30:31], v[178:179] op_sel_hi:[1,0,1]
	v_pk_fma_f32 v[92:93], v[212:213], s[30:31], v[180:181] op_sel_hi:[1,0,1]
	v_pk_fma_f32 v[94:95], v[214:215], s[30:31], v[182:183] op_sel_hi:[1,0,1]
	v_pk_fma_f32 v[96:97], v[216:217], s[30:31], v[184:185] op_sel_hi:[1,0,1]
	s_mov_b32 s70, 0x80000
	v_lshl_add_u64 v[150:151], v[230:231], 0, s[70:71]
	v_lshl_add_u64 v[220:221], v[150:151], 0, s[44:45]
	v_lshl_add_u64 v[222:223], v[220:221], 0, s[44:45]
	v_lshl_add_u64 v[224:225], v[222:223], 0, s[44:45]
	global_load_dwordx4 v[186:189], v[150:151], off
	global_load_dwordx4 v[190:193], v[150:151], off offset:16
	global_load_dwordx4 v[194:197], v[220:221], off
	global_load_dwordx4 v[198:201], v[220:221], off offset:16
	global_load_dwordx4 v[202:205], v[222:223], off
	global_load_dwordx4 v[206:209], v[222:223], off offset:16
	global_load_dwordx4 v[210:213], v[224:225], off
	global_load_dwordx4 v[214:217], v[224:225], off offset:16
	ds_write2st64_b32 v152, v34, v35 offset1:2
	ds_write2st64_b32 v152, v36, v37 offset0:4 offset1:6
	ds_write2st64_b32 v149, v38, v39 offset1:2
	ds_write2st64_b32 v149, v40, v41 offset0:4 offset1:6
	ds_write2st64_b32 v152, v42, v43 offset0:32 offset1:34
	ds_write2st64_b32 v152, v44, v45 offset0:36 offset1:38
	ds_write2st64_b32 v149, v46, v47 offset0:32 offset1:34
	ds_write2st64_b32 v149, v48, v49 offset0:36 offset1:38
	ds_write2st64_b32 v152, v50, v51 offset0:64 offset1:66
	ds_write2st64_b32 v152, v52, v53 offset0:68 offset1:70
	ds_write2st64_b32 v149, v54, v55 offset0:64 offset1:66
	ds_write2st64_b32 v149, v56, v57 offset0:68 offset1:70
	ds_write2st64_b32 v152, v58, v59 offset0:96 offset1:98
	ds_write2st64_b32 v152, v60, v61 offset0:100 offset1:102
	ds_write2st64_b32 v149, v62, v63 offset0:96 offset1:98
	ds_write2st64_b32 v149, v64, v65 offset0:100 offset1:102
	s_waitcnt lgkmcnt(0)
	s_barrier
	ds_read_b128 v[154:157], v146
	ds_read_b128 v[158:161], v147
	ds_read_b128 v[162:165], v145
	ds_read_b128 v[166:169], v144
	ds_read_b128 v[170:173], v143
	ds_read_b128 v[174:177], v142
	ds_read_b128 v[178:181], v141
	ds_read_b128 v[182:185], v140
	s_waitcnt vmcnt(0) lgkmcnt(0)
	s_barrier
	v_pk_fma_f32 v[34:35], v[186:187], s[30:31], v[154:155] op_sel_hi:[1,0,1]
	v_pk_fma_f32 v[36:37], v[188:189], s[30:31], v[156:157] op_sel_hi:[1,0,1]
	v_pk_fma_f32 v[38:39], v[190:191], s[30:31], v[158:159] op_sel_hi:[1,0,1]
	v_pk_fma_f32 v[40:41], v[192:193], s[30:31], v[160:161] op_sel_hi:[1,0,1]
	v_pk_fma_f32 v[42:43], v[194:195], s[30:31], v[162:163] op_sel_hi:[1,0,1]
	v_pk_fma_f32 v[44:45], v[196:197], s[30:31], v[164:165] op_sel_hi:[1,0,1]
	v_pk_fma_f32 v[46:47], v[198:199], s[30:31], v[166:167] op_sel_hi:[1,0,1]
	v_pk_fma_f32 v[48:49], v[200:201], s[30:31], v[168:169] op_sel_hi:[1,0,1]
	v_pk_fma_f32 v[50:51], v[202:203], s[30:31], v[170:171] op_sel_hi:[1,0,1]
	v_pk_fma_f32 v[52:53], v[204:205], s[30:31], v[172:173] op_sel_hi:[1,0,1]
	v_pk_fma_f32 v[54:55], v[206:207], s[30:31], v[174:175] op_sel_hi:[1,0,1]
	v_pk_fma_f32 v[56:57], v[208:209], s[30:31], v[176:177] op_sel_hi:[1,0,1]
	v_pk_fma_f32 v[58:59], v[210:211], s[30:31], v[178:179] op_sel_hi:[1,0,1]
	v_pk_fma_f32 v[60:61], v[212:213], s[30:31], v[180:181] op_sel_hi:[1,0,1]
	v_pk_fma_f32 v[62:63], v[214:215], s[30:31], v[182:183] op_sel_hi:[1,0,1]
	v_pk_fma_f32 v[64:65], v[216:217], s[30:31], v[184:185] op_sel_hi:[1,0,1]
	s_mov_b32 s70, 0x80200
	v_lshl_add_u64 v[150:151], v[230:231], 0, s[70:71]
	v_lshl_add_u64 v[220:221], v[150:151], 0, s[44:45]
	v_lshl_add_u64 v[222:223], v[220:221], 0, s[44:45]
	v_lshl_add_u64 v[224:225], v[222:223], 0, s[44:45]
	global_load_dwordx4 v[186:189], v[150:151], off
	global_load_dwordx4 v[190:193], v[150:151], off offset:16
	global_load_dwordx4 v[194:197], v[220:221], off
	global_load_dwordx4 v[198:201], v[220:221], off offset:16
	global_load_dwordx4 v[202:205], v[222:223], off
	global_load_dwordx4 v[206:209], v[222:223], off offset:16
	global_load_dwordx4 v[210:213], v[224:225], off
	global_load_dwordx4 v[214:217], v[224:225], off offset:16
	ds_write2st64_b32 v152, v2, v3 offset1:2
	ds_write2st64_b32 v152, v4, v5 offset0:4 offset1:6
	ds_write2st64_b32 v149, v6, v7 offset1:2
	ds_write2st64_b32 v149, v8, v9 offset0:4 offset1:6
	ds_write2st64_b32 v152, v10, v11 offset0:32 offset1:34
	ds_write2st64_b32 v152, v12, v13 offset0:36 offset1:38
	ds_write2st64_b32 v149, v14, v15 offset0:32 offset1:34
	ds_write2st64_b32 v149, v16, v17 offset0:36 offset1:38
	ds_write2st64_b32 v152, v18, v19 offset0:64 offset1:66
	ds_write2st64_b32 v152, v20, v21 offset0:68 offset1:70
	ds_write2st64_b32 v149, v22, v23 offset0:64 offset1:66
	ds_write2st64_b32 v149, v24, v25 offset0:68 offset1:70
	ds_write2st64_b32 v152, v26, v27 offset0:96 offset1:98
	ds_write2st64_b32 v152, v28, v29 offset0:100 offset1:102
	ds_write2st64_b32 v149, v30, v31 offset0:96 offset1:98
	ds_write2st64_b32 v149, v32, v33 offset0:100 offset1:102
	s_waitcnt lgkmcnt(0)
	s_barrier
	ds_read_b128 v[154:157], v146
	ds_read_b128 v[158:161], v147
	ds_read_b128 v[162:165], v145
	ds_read_b128 v[166:169], v144
	ds_read_b128 v[170:173], v143
	ds_read_b128 v[174:177], v142
	ds_read_b128 v[178:181], v141
	ds_read_b128 v[182:185], v140
	s_waitcnt vmcnt(0) lgkmcnt(0)
	v_pk_fma_f32 v[2:3], v[186:187], s[30:31], v[154:155] op_sel_hi:[1,0,1]
	v_pk_fma_f32 v[4:5], v[188:189], s[30:31], v[156:157] op_sel_hi:[1,0,1]
	v_pk_fma_f32 v[6:7], v[190:191], s[30:31], v[158:159] op_sel_hi:[1,0,1]
	v_pk_fma_f32 v[8:9], v[192:193], s[30:31], v[160:161] op_sel_hi:[1,0,1]
	v_pk_fma_f32 v[10:11], v[194:195], s[30:31], v[162:163] op_sel_hi:[1,0,1]
	v_pk_fma_f32 v[12:13], v[196:197], s[30:31], v[164:165] op_sel_hi:[1,0,1]
	v_pk_fma_f32 v[14:15], v[198:199], s[30:31], v[166:167] op_sel_hi:[1,0,1]
	v_pk_fma_f32 v[16:17], v[200:201], s[30:31], v[168:169] op_sel_hi:[1,0,1]
	v_pk_fma_f32 v[18:19], v[202:203], s[30:31], v[170:171] op_sel_hi:[1,0,1]
	v_pk_fma_f32 v[20:21], v[204:205], s[30:31], v[172:173] op_sel_hi:[1,0,1]
	v_pk_fma_f32 v[22:23], v[206:207], s[30:31], v[174:175] op_sel_hi:[1,0,1]
	v_pk_fma_f32 v[24:25], v[208:209], s[30:31], v[176:177] op_sel_hi:[1,0,1]
	v_pk_fma_f32 v[26:27], v[210:211], s[30:31], v[178:179] op_sel_hi:[1,0,1]
	v_pk_fma_f32 v[28:29], v[212:213], s[30:31], v[180:181] op_sel_hi:[1,0,1]
	v_pk_fma_f32 v[30:31], v[214:215], s[30:31], v[182:183] op_sel_hi:[1,0,1]
	v_pk_fma_f32 v[32:33], v[216:217], s[30:31], v[184:185] op_sel_hi:[1,0,1]
	v_readlane_b32 s86, v253, 8
	v_readlane_b32 s87, v253, 9
	v_readlane_b32 s92, v253, 10
	v_readlane_b32 s93, v253, 11
	s_lshl_b32 s0, s38, 3
	s_add_u32 s44, s62, 0xf000000
	s_addc_u32 s45, s63, 0
	s_add_u32 s44, s44, s0
	s_addc_u32 s45, s45, 0
	v_lshl_add_u64 v[230:231], s[66:67], 0, v[228:229]
	v_lshrrev_b64 v[222:223], 1, v[228:229]
	v_lshl_add_u64 v[222:223], s[60:61], 0, v[222:223]
	s_nop 2
	global_load_dwordx4 v[186:189], v226, s[86:87] offset:0
	global_load_dwordx4 v[190:193], v226, s[86:87] offset:16
	global_load_dwordx4 v[194:197], v226, s[86:87] offset:512
	global_load_dwordx4 v[198:201], v226, s[86:87] offset:528
	global_load_dwordx4 v[202:205], v226, s[92:93] offset:0
	global_load_dwordx4 v[206:209], v226, s[92:93] offset:16
	global_load_dwordx4 v[210:213], v226, s[92:93] offset:512
	global_load_dwordx4 v[214:217], v226, s[92:93] offset:528
	v_pk_add_f32 v[154:155], v[98:99], v[100:101]
	v_pk_add_f32 v[156:157], v[106:107], v[108:109]
	v_pk_add_f32 v[158:159], v[114:115], v[116:117]
	v_pk_add_f32 v[160:161], v[122:123], v[124:125]
	v_pk_add_f32 v[162:163], v[34:35], v[36:37]
	v_pk_add_f32 v[164:165], v[42:43], v[44:45]
	v_pk_add_f32 v[166:167], v[50:51], v[52:53]
	v_pk_add_f32 v[168:169], v[58:59], v[60:61]
	v_pk_add_f32 v[154:155], v[154:155], v[102:103]
	v_pk_add_f32 v[156:157], v[156:157], v[110:111]
	v_pk_add_f32 v[158:159], v[158:159], v[118:119]
	v_pk_add_f32 v[160:161], v[160:161], v[126:127]
	v_pk_add_f32 v[162:163], v[162:163], v[38:39]
	v_pk_add_f32 v[164:165], v[164:165], v[46:47]
	v_pk_add_f32 v[166:167], v[166:167], v[54:55]
	v_pk_add_f32 v[168:169], v[168:169], v[62:63]
	v_pk_add_f32 v[154:155], v[154:155], v[104:105]
	v_pk_add_f32 v[156:157], v[156:157], v[112:113]
	v_pk_add_f32 v[158:159], v[158:159], v[120:121]
	v_pk_add_f32 v[160:161], v[160:161], v[128:129]
	v_pk_add_f32 v[162:163], v[162:163], v[40:41]
	v_pk_add_f32 v[164:165], v[164:165], v[48:49]
	v_pk_add_f32 v[166:167], v[166:167], v[56:57]
	v_pk_add_f32 v[168:169], v[168:169], v[64:65]
	v_pk_add_f32 v[154:155], v[154:155], v[66:67]
	v_pk_add_f32 v[156:157], v[156:157], v[74:75]
	v_pk_add_f32 v[158:159], v[158:159], v[82:83]
	v_pk_add_f32 v[160:161], v[160:161], v[90:91]
	v_pk_add_f32 v[162:163], v[162:163], v[2:3]
	v_pk_add_f32 v[164:165], v[164:165], v[10:11]
	v_pk_add_f32 v[166:167], v[166:167], v[18:19]
	v_pk_add_f32 v[168:169], v[168:169], v[26:27]
	v_pk_add_f32 v[154:155], v[154:155], v[68:69]
	v_pk_add_f32 v[156:157], v[156:157], v[76:77]
	v_pk_add_f32 v[158:159], v[158:159], v[84:85]
	v_pk_add_f32 v[160:161], v[160:161], v[92:93]
	v_pk_add_f32 v[162:163], v[162:163], v[4:5]
	v_pk_add_f32 v[164:165], v[164:165], v[12:13]
	v_pk_add_f32 v[166:167], v[166:167], v[20:21]
	v_pk_add_f32 v[168:169], v[168:169], v[28:29]
	v_pk_add_f32 v[154:155], v[154:155], v[70:71]
	v_pk_add_f32 v[156:157], v[156:157], v[78:79]
	v_pk_add_f32 v[158:159], v[158:159], v[86:87]
	v_pk_add_f32 v[160:161], v[160:161], v[94:95]
	v_pk_add_f32 v[162:163], v[162:163], v[6:7]
	v_pk_add_f32 v[164:165], v[164:165], v[14:15]
	v_pk_add_f32 v[166:167], v[166:167], v[22:23]
	v_pk_add_f32 v[168:169], v[168:169], v[30:31]
	v_pk_add_f32 v[154:155], v[154:155], v[72:73]
	v_pk_add_f32 v[156:157], v[156:157], v[80:81]
	v_pk_add_f32 v[158:159], v[158:159], v[88:89]
	v_pk_add_f32 v[160:161], v[160:161], v[96:97]
	v_pk_add_f32 v[162:163], v[162:163], v[8:9]
	v_pk_add_f32 v[164:165], v[164:165], v[16:17]
	v_pk_add_f32 v[166:167], v[166:167], v[24:25]
	v_pk_add_f32 v[168:169], v[168:169], v[32:33]
	v_add_f32_e32 v132, v154, v155
	v_add_f32_e32 v134, v156, v157
	v_add_f32_e32 v136, v158, v159
	v_add_f32_e32 v138, v160, v161
	v_add_f32_e32 v232, v162, v163
	v_add_f32_e32 v234, v164, v165
	v_add_f32_e32 v236, v166, v167
	v_add_f32_e32 v150, v168, v169
	v_add_f32_dpp v132, v132, v132 quad_perm:[1,0,3,2] row_mask:0xf bank_mask:0xf
	v_add_f32_dpp v134, v134, v134 quad_perm:[1,0,3,2] row_mask:0xf bank_mask:0xf
	v_add_f32_dpp v136, v136, v136 quad_perm:[1,0,3,2] row_mask:0xf bank_mask:0xf
	v_add_f32_dpp v138, v138, v138 quad_perm:[1,0,3,2] row_mask:0xf bank_mask:0xf
	v_add_f32_dpp v232, v232, v232 quad_perm:[1,0,3,2] row_mask:0xf bank_mask:0xf
	v_add_f32_dpp v234, v234, v234 quad_perm:[1,0,3,2] row_mask:0xf bank_mask:0xf
	v_add_f32_dpp v236, v236, v236 quad_perm:[1,0,3,2] row_mask:0xf bank_mask:0xf
	v_add_f32_dpp v150, v150, v150 quad_perm:[1,0,3,2] row_mask:0xf bank_mask:0xf
	v_add_f32_dpp v132, v132, v132 quad_perm:[2,3,0,1] row_mask:0xf bank_mask:0xf
	v_add_f32_dpp v134, v134, v134 quad_perm:[2,3,0,1] row_mask:0xf bank_mask:0xf
	v_add_f32_dpp v136, v136, v136 quad_perm:[2,3,0,1] row_mask:0xf bank_mask:0xf
	v_add_f32_dpp v138, v138, v138 quad_perm:[2,3,0,1] row_mask:0xf bank_mask:0xf
	v_add_f32_dpp v232, v232, v232 quad_perm:[2,3,0,1] row_mask:0xf bank_mask:0xf
	v_add_f32_dpp v234, v234, v234 quad_perm:[2,3,0,1] row_mask:0xf bank_mask:0xf
	v_add_f32_dpp v236, v236, v236 quad_perm:[2,3,0,1] row_mask:0xf bank_mask:0xf
	v_add_f32_dpp v150, v150, v150 quad_perm:[2,3,0,1] row_mask:0xf bank_mask:0xf
	v_add_f32_dpp v132, v132, v132 row_half_mirror row_mask:0xf bank_mask:0xf
	v_add_f32_dpp v134, v134, v134 row_half_mirror row_mask:0xf bank_mask:0xf
	v_add_f32_dpp v136, v136, v136 row_half_mirror row_mask:0xf bank_mask:0xf
	v_add_f32_dpp v138, v138, v138 row_half_mirror row_mask:0xf bank_mask:0xf
	v_add_f32_dpp v232, v232, v232 row_half_mirror row_mask:0xf bank_mask:0xf
	v_add_f32_dpp v234, v234, v234 row_half_mirror row_mask:0xf bank_mask:0xf
	v_add_f32_dpp v236, v236, v236 row_half_mirror row_mask:0xf bank_mask:0xf
	v_add_f32_dpp v150, v150, v150 row_half_mirror row_mask:0xf bank_mask:0xf
	v_add_f32_dpp v132, v132, v132 row_mirror row_mask:0xf bank_mask:0xf
	v_add_f32_dpp v134, v134, v134 row_mirror row_mask:0xf bank_mask:0xf
	v_add_f32_dpp v136, v136, v136 row_mirror row_mask:0xf bank_mask:0xf
	v_add_f32_dpp v138, v138, v138 row_mirror row_mask:0xf bank_mask:0xf
	v_add_f32_dpp v232, v232, v232 row_mirror row_mask:0xf bank_mask:0xf
	v_add_f32_dpp v234, v234, v234 row_mirror row_mask:0xf bank_mask:0xf
	v_add_f32_dpp v236, v236, v236 row_mirror row_mask:0xf bank_mask:0xf
	v_add_f32_dpp v150, v150, v150 row_mirror row_mask:0xf bank_mask:0xf
	v_mul_f32_e32 v132, 0x3b800000, v132
	v_mul_f32_e32 v134, 0x3b800000, v134
	v_mul_f32_e32 v136, 0x3b800000, v136
	v_mul_f32_e32 v138, 0x3b800000, v138
	v_mul_f32_e32 v232, 0x3b800000, v232
	v_mul_f32_e32 v234, 0x3b800000, v234
	v_mul_f32_e32 v236, 0x3b800000, v236
	v_mul_f32_e32 v150, 0x3b800000, v150
	v_pk_add_f32 v[218:219], v[98:99], v[132:133] op_sel_hi:[1,0] neg_lo:[0,1] neg_hi:[0,1]
	v_pk_mul_f32 v[170:171], v[218:219], v[218:219]
	v_pk_add_f32 v[220:221], v[106:107], v[134:135] op_sel_hi:[1,0] neg_lo:[0,1] neg_hi:[0,1]
	v_pk_mul_f32 v[172:173], v[220:221], v[220:221]
	v_pk_add_f32 v[218:219], v[114:115], v[136:137] op_sel_hi:[1,0] neg_lo:[0,1] neg_hi:[0,1]
	v_pk_mul_f32 v[174:175], v[218:219], v[218:219]
	v_pk_add_f32 v[220:221], v[122:123], v[138:139] op_sel_hi:[1,0] neg_lo:[0,1] neg_hi:[0,1]
	v_pk_mul_f32 v[176:177], v[220:221], v[220:221]
	v_pk_add_f32 v[218:219], v[34:35], v[232:233] op_sel_hi:[1,0] neg_lo:[0,1] neg_hi:[0,1]
	v_pk_mul_f32 v[178:179], v[218:219], v[218:219]
	v_pk_add_f32 v[220:221], v[42:43], v[234:235] op_sel_hi:[1,0] neg_lo:[0,1] neg_hi:[0,1]
	v_pk_mul_f32 v[180:181], v[220:221], v[220:221]
	v_pk_add_f32 v[218:219], v[50:51], v[236:237] op_sel_hi:[1,0] neg_lo:[0,1] neg_hi:[0,1]
	v_pk_mul_f32 v[182:183], v[218:219], v[218:219]
	v_pk_add_f32 v[220:221], v[58:59], v[150:151] op_sel_hi:[1,0] neg_lo:[0,1] neg_hi:[0,1]
	v_pk_mul_f32 v[184:185], v[220:221], v[220:221]
	v_pk_add_f32 v[218:219], v[100:101], v[132:133] op_sel_hi:[1,0] neg_lo:[0,1] neg_hi:[0,1]
	v_pk_fma_f32 v[170:171], v[218:219], v[218:219], v[170:171]
	v_pk_add_f32 v[220:221], v[108:109], v[134:135] op_sel_hi:[1,0] neg_lo:[0,1] neg_hi:[0,1]
	v_pk_fma_f32 v[172:173], v[220:221], v[220:221], v[172:173]
	v_pk_add_f32 v[218:219], v[116:117], v[136:137] op_sel_hi:[1,0] neg_lo:[0,1] neg_hi:[0,1]
	v_pk_fma_f32 v[174:175], v[218:219], v[218:219], v[174:175]
	v_pk_add_f32 v[220:221], v[124:125], v[138:139] op_sel_hi:[1,0] neg_lo:[0,1] neg_hi:[0,1]
	v_pk_fma_f32 v[176:177], v[220:221], v[220:221], v[176:177]
	v_pk_add_f32 v[218:219], v[36:37], v[232:233] op_sel_hi:[1,0] neg_lo:[0,1] neg_hi:[0,1]
	v_pk_fma_f32 v[178:179], v[218:219], v[218:219], v[178:179]
	v_pk_add_f32 v[220:221], v[44:45], v[234:235] op_sel_hi:[1,0] neg_lo:[0,1] neg_hi:[0,1]
	v_pk_fma_f32 v[180:181], v[220:221], v[220:221], v[180:181]
	v_pk_add_f32 v[218:219], v[52:53], v[236:237] op_sel_hi:[1,0] neg_lo:[0,1] neg_hi:[0,1]
	v_pk_fma_f32 v[182:183], v[218:219], v[218:219], v[182:183]
	v_pk_add_f32 v[220:221], v[60:61], v[150:151] op_sel_hi:[1,0] neg_lo:[0,1] neg_hi:[0,1]
	v_pk_fma_f32 v[184:185], v[220:221], v[220:221], v[184:185]
	v_pk_add_f32 v[218:219], v[102:103], v[132:133] op_sel_hi:[1,0] neg_lo:[0,1] neg_hi:[0,1]
	v_pk_fma_f32 v[170:171], v[218:219], v[218:219], v[170:171]
	v_pk_add_f32 v[220:221], v[110:111], v[134:135] op_sel_hi:[1,0] neg_lo:[0,1] neg_hi:[0,1]
	v_pk_fma_f32 v[172:173], v[220:221], v[220:221], v[172:173]
	v_pk_add_f32 v[218:219], v[118:119], v[136:137] op_sel_hi:[1,0] neg_lo:[0,1] neg_hi:[0,1]
	v_pk_fma_f32 v[174:175], v[218:219], v[218:219], v[174:175]
	v_pk_add_f32 v[220:221], v[126:127], v[138:139] op_sel_hi:[1,0] neg_lo:[0,1] neg_hi:[0,1]
	v_pk_fma_f32 v[176:177], v[220:221], v[220:221], v[176:177]
	v_pk_add_f32 v[218:219], v[38:39], v[232:233] op_sel_hi:[1,0] neg_lo:[0,1] neg_hi:[0,1]
	v_pk_fma_f32 v[178:179], v[218:219], v[218:219], v[178:179]
	v_pk_add_f32 v[220:221], v[46:47], v[234:235] op_sel_hi:[1,0] neg_lo:[0,1] neg_hi:[0,1]
	v_pk_fma_f32 v[180:181], v[220:221], v[220:221], v[180:181]
	v_pk_add_f32 v[218:219], v[54:55], v[236:237] op_sel_hi:[1,0] neg_lo:[0,1] neg_hi:[0,1]
	v_pk_fma_f32 v[182:183], v[218:219], v[218:219], v[182:183]
	v_pk_add_f32 v[220:221], v[62:63], v[150:151] op_sel_hi:[1,0] neg_lo:[0,1] neg_hi:[0,1]
	v_pk_fma_f32 v[184:185], v[220:221], v[220:221], v[184:185]
	v_pk_add_f32 v[218:219], v[104:105], v[132:133] op_sel_hi:[1,0] neg_lo:[0,1] neg_hi:[0,1]
	v_pk_fma_f32 v[170:171], v[218:219], v[218:219], v[170:171]
	v_pk_add_f32 v[220:221], v[112:113], v[134:135] op_sel_hi:[1,0] neg_lo:[0,1] neg_hi:[0,1]
	v_pk_fma_f32 v[172:173], v[220:221], v[220:221], v[172:173]
	v_pk_add_f32 v[218:219], v[120:121], v[136:137] op_sel_hi:[1,0] neg_lo:[0,1] neg_hi:[0,1]
	v_pk_fma_f32 v[174:175], v[218:219], v[218:219], v[174:175]
	v_pk_add_f32 v[220:221], v[128:129], v[138:139] op_sel_hi:[1,0] neg_lo:[0,1] neg_hi:[0,1]
	v_pk_fma_f32 v[176:177], v[220:221], v[220:221], v[176:177]
	v_pk_add_f32 v[218:219], v[40:41], v[232:233] op_sel_hi:[1,0] neg_lo:[0,1] neg_hi:[0,1]
	v_pk_fma_f32 v[178:179], v[218:219], v[218:219], v[178:179]
	v_pk_add_f32 v[220:221], v[48:49], v[234:235] op_sel_hi:[1,0] neg_lo:[0,1] neg_hi:[0,1]
	v_pk_fma_f32 v[180:181], v[220:221], v[220:221], v[180:181]
	v_pk_add_f32 v[218:219], v[56:57], v[236:237] op_sel_hi:[1,0] neg_lo:[0,1] neg_hi:[0,1]
	v_pk_fma_f32 v[182:183], v[218:219], v[218:219], v[182:183]
	v_pk_add_f32 v[220:221], v[64:65], v[150:151] op_sel_hi:[1,0] neg_lo:[0,1] neg_hi:[0,1]
	v_pk_fma_f32 v[184:185], v[220:221], v[220:221], v[184:185]
	v_pk_add_f32 v[218:219], v[66:67], v[132:133] op_sel_hi:[1,0] neg_lo:[0,1] neg_hi:[0,1]
	v_pk_fma_f32 v[170:171], v[218:219], v[218:219], v[170:171]
	v_pk_add_f32 v[220:221], v[74:75], v[134:135] op_sel_hi:[1,0] neg_lo:[0,1] neg_hi:[0,1]
	v_pk_fma_f32 v[172:173], v[220:221], v[220:221], v[172:173]
	v_pk_add_f32 v[218:219], v[82:83], v[136:137] op_sel_hi:[1,0] neg_lo:[0,1] neg_hi:[0,1]
	v_pk_fma_f32 v[174:175], v[218:219], v[218:219], v[174:175]
	v_pk_add_f32 v[220:221], v[90:91], v[138:139] op_sel_hi:[1,0] neg_lo:[0,1] neg_hi:[0,1]
	v_pk_fma_f32 v[176:177], v[220:221], v[220:221], v[176:177]
	v_pk_add_f32 v[218:219], v[2:3], v[232:233] op_sel_hi:[1,0] neg_lo:[0,1] neg_hi:[0,1]
	v_pk_fma_f32 v[178:179], v[218:219], v[218:219], v[178:179]
	v_pk_add_f32 v[220:221], v[10:11], v[234:235] op_sel_hi:[1,0] neg_lo:[0,1] neg_hi:[0,1]
	v_pk_fma_f32 v[180:181], v[220:221], v[220:221], v[180:181]
	v_pk_add_f32 v[218:219], v[18:19], v[236:237] op_sel_hi:[1,0] neg_lo:[0,1] neg_hi:[0,1]
	v_pk_fma_f32 v[182:183], v[218:219], v[218:219], v[182:183]
	v_pk_add_f32 v[220:221], v[26:27], v[150:151] op_sel_hi:[1,0] neg_lo:[0,1] neg_hi:[0,1]
	v_pk_fma_f32 v[184:185], v[220:221], v[220:221], v[184:185]
	v_pk_add_f32 v[218:219], v[68:69], v[132:133] op_sel_hi:[1,0] neg_lo:[0,1] neg_hi:[0,1]
	v_pk_fma_f32 v[170:171], v[218:219], v[218:219], v[170:171]
	v_pk_add_f32 v[220:221], v[76:77], v[134:135] op_sel_hi:[1,0] neg_lo:[0,1] neg_hi:[0,1]
	v_pk_fma_f32 v[172:173], v[220:221], v[220:221], v[172:173]
	v_pk_add_f32 v[218:219], v[84:85], v[136:137] op_sel_hi:[1,0] neg_lo:[0,1] neg_hi:[0,1]
	v_pk_fma_f32 v[174:175], v[218:219], v[218:219], v[174:175]
	v_pk_add_f32 v[220:221], v[92:93], v[138:139] op_sel_hi:[1,0] neg_lo:[0,1] neg_hi:[0,1]
	v_pk_fma_f32 v[176:177], v[220:221], v[220:221], v[176:177]
	v_pk_add_f32 v[218:219], v[4:5], v[232:233] op_sel_hi:[1,0] neg_lo:[0,1] neg_hi:[0,1]
	v_pk_fma_f32 v[178:179], v[218:219], v[218:219], v[178:179]
	v_pk_add_f32 v[220:221], v[12:13], v[234:235] op_sel_hi:[1,0] neg_lo:[0,1] neg_hi:[0,1]
	v_pk_fma_f32 v[180:181], v[220:221], v[220:221], v[180:181]
	v_pk_add_f32 v[218:219], v[20:21], v[236:237] op_sel_hi:[1,0] neg_lo:[0,1] neg_hi:[0,1]
	v_pk_fma_f32 v[182:183], v[218:219], v[218:219], v[182:183]
	v_pk_add_f32 v[220:221], v[28:29], v[150:151] op_sel_hi:[1,0] neg_lo:[0,1] neg_hi:[0,1]
	v_pk_fma_f32 v[184:185], v[220:221], v[220:221], v[184:185]
	v_pk_add_f32 v[218:219], v[70:71], v[132:133] op_sel_hi:[1,0] neg_lo:[0,1] neg_hi:[0,1]
	v_pk_fma_f32 v[170:171], v[218:219], v[218:219], v[170:171]
	v_pk_add_f32 v[220:221], v[78:79], v[134:135] op_sel_hi:[1,0] neg_lo:[0,1] neg_hi:[0,1]
	v_pk_fma_f32 v[172:173], v[220:221], v[220:221], v[172:173]
	v_pk_add_f32 v[218:219], v[86:87], v[136:137] op_sel_hi:[1,0] neg_lo:[0,1] neg_hi:[0,1]
	v_pk_fma_f32 v[174:175], v[218:219], v[218:219], v[174:175]
	v_pk_add_f32 v[220:221], v[94:95], v[138:139] op_sel_hi:[1,0] neg_lo:[0,1] neg_hi:[0,1]
	v_pk_fma_f32 v[176:177], v[220:221], v[220:221], v[176:177]
	v_pk_add_f32 v[218:219], v[6:7], v[232:233] op_sel_hi:[1,0] neg_lo:[0,1] neg_hi:[0,1]
	v_pk_fma_f32 v[178:179], v[218:219], v[218:219], v[178:179]
	v_pk_add_f32 v[220:221], v[14:15], v[234:235] op_sel_hi:[1,0] neg_lo:[0,1] neg_hi:[0,1]
	v_pk_fma_f32 v[180:181], v[220:221], v[220:221], v[180:181]
	v_pk_add_f32 v[218:219], v[22:23], v[236:237] op_sel_hi:[1,0] neg_lo:[0,1] neg_hi:[0,1]
	v_pk_fma_f32 v[182:183], v[218:219], v[218:219], v[182:183]
	v_pk_add_f32 v[220:221], v[30:31], v[150:151] op_sel_hi:[1,0] neg_lo:[0,1] neg_hi:[0,1]
	v_pk_fma_f32 v[184:185], v[220:221], v[220:221], v[184:185]
	v_pk_add_f32 v[218:219], v[72:73], v[132:133] op_sel_hi:[1,0] neg_lo:[0,1] neg_hi:[0,1]
	v_pk_fma_f32 v[170:171], v[218:219], v[218:219], v[170:171]
	v_pk_add_f32 v[220:221], v[80:81], v[134:135] op_sel_hi:[1,0] neg_lo:[0,1] neg_hi:[0,1]
	v_pk_fma_f32 v[172:173], v[220:221], v[220:221], v[172:173]
	v_pk_add_f32 v[218:219], v[88:89], v[136:137] op_sel_hi:[1,0] neg_lo:[0,1] neg_hi:[0,1]
	v_pk_fma_f32 v[174:175], v[218:219], v[218:219], v[174:175]
	v_pk_add_f32 v[220:221], v[96:97], v[138:139] op_sel_hi:[1,0] neg_lo:[0,1] neg_hi:[0,1]
	v_pk_fma_f32 v[176:177], v[220:221], v[220:221], v[176:177]
	v_pk_add_f32 v[218:219], v[8:9], v[232:233] op_sel_hi:[1,0] neg_lo:[0,1] neg_hi:[0,1]
	v_pk_fma_f32 v[178:179], v[218:219], v[218:219], v[178:179]
	v_pk_add_f32 v[220:221], v[16:17], v[234:235] op_sel_hi:[1,0] neg_lo:[0,1] neg_hi:[0,1]
	v_pk_fma_f32 v[180:181], v[220:221], v[220:221], v[180:181]
	v_pk_add_f32 v[218:219], v[24:25], v[236:237] op_sel_hi:[1,0] neg_lo:[0,1] neg_hi:[0,1]
	v_pk_fma_f32 v[182:183], v[218:219], v[218:219], v[182:183]
	v_pk_add_f32 v[220:221], v[32:33], v[150:151] op_sel_hi:[1,0] neg_lo:[0,1] neg_hi:[0,1]
	v_pk_fma_f32 v[184:185], v[220:221], v[220:221], v[184:185]
	v_add_f32_e32 v133, v170, v171
	v_add_f32_e32 v135, v172, v173
	v_add_f32_e32 v137, v174, v175
	v_add_f32_e32 v139, v176, v177
	v_add_f32_e32 v233, v178, v179
	v_add_f32_e32 v235, v180, v181
	v_add_f32_e32 v237, v182, v183
	v_add_f32_e32 v151, v184, v185
	v_add_f32_dpp v133, v133, v133 quad_perm:[1,0,3,2] row_mask:0xf bank_mask:0xf
	v_add_f32_dpp v135, v135, v135 quad_perm:[1,0,3,2] row_mask:0xf bank_mask:0xf
	v_add_f32_dpp v137, v137, v137 quad_perm:[1,0,3,2] row_mask:0xf bank_mask:0xf
	v_add_f32_dpp v139, v139, v139 quad_perm:[1,0,3,2] row_mask:0xf bank_mask:0xf
	v_add_f32_dpp v233, v233, v233 quad_perm:[1,0,3,2] row_mask:0xf bank_mask:0xf
	v_add_f32_dpp v235, v235, v235 quad_perm:[1,0,3,2] row_mask:0xf bank_mask:0xf
	v_add_f32_dpp v237, v237, v237 quad_perm:[1,0,3,2] row_mask:0xf bank_mask:0xf
	v_add_f32_dpp v151, v151, v151 quad_perm:[1,0,3,2] row_mask:0xf bank_mask:0xf
	v_add_f32_dpp v133, v133, v133 quad_perm:[2,3,0,1] row_mask:0xf bank_mask:0xf
	v_add_f32_dpp v135, v135, v135 quad_perm:[2,3,0,1] row_mask:0xf bank_mask:0xf
	v_add_f32_dpp v137, v137, v137 quad_perm:[2,3,0,1] row_mask:0xf bank_mask:0xf
	v_add_f32_dpp v139, v139, v139 quad_perm:[2,3,0,1] row_mask:0xf bank_mask:0xf
	v_add_f32_dpp v233, v233, v233 quad_perm:[2,3,0,1] row_mask:0xf bank_mask:0xf
	v_add_f32_dpp v235, v235, v235 quad_perm:[2,3,0,1] row_mask:0xf bank_mask:0xf
	v_add_f32_dpp v237, v237, v237 quad_perm:[2,3,0,1] row_mask:0xf bank_mask:0xf
	v_add_f32_dpp v151, v151, v151 quad_perm:[2,3,0,1] row_mask:0xf bank_mask:0xf
	v_add_f32_dpp v133, v133, v133 row_half_mirror row_mask:0xf bank_mask:0xf
	v_add_f32_dpp v135, v135, v135 row_half_mirror row_mask:0xf bank_mask:0xf
	v_add_f32_dpp v137, v137, v137 row_half_mirror row_mask:0xf bank_mask:0xf
	v_add_f32_dpp v139, v139, v139 row_half_mirror row_mask:0xf bank_mask:0xf
	v_add_f32_dpp v233, v233, v233 row_half_mirror row_mask:0xf bank_mask:0xf
	v_add_f32_dpp v235, v235, v235 row_half_mirror row_mask:0xf bank_mask:0xf
	v_add_f32_dpp v237, v237, v237 row_half_mirror row_mask:0xf bank_mask:0xf
	v_add_f32_dpp v151, v151, v151 row_half_mirror row_mask:0xf bank_mask:0xf
	v_add_f32_dpp v133, v133, v133 row_mirror row_mask:0xf bank_mask:0xf
	v_add_f32_dpp v135, v135, v135 row_mirror row_mask:0xf bank_mask:0xf
	v_add_f32_dpp v137, v137, v137 row_mirror row_mask:0xf bank_mask:0xf
	v_add_f32_dpp v139, v139, v139 row_mirror row_mask:0xf bank_mask:0xf
	v_add_f32_dpp v233, v233, v233 row_mirror row_mask:0xf bank_mask:0xf
	v_add_f32_dpp v235, v235, v235 row_mirror row_mask:0xf bank_mask:0xf
	v_add_f32_dpp v237, v237, v237 row_mirror row_mask:0xf bank_mask:0xf
	v_add_f32_dpp v151, v151, v151 row_mirror row_mask:0xf bank_mask:0xf
	s_lshr_b32 s0, s38, 8
	s_lshl_b32 s0, s0, 13
	s_add_u32 s74, s62, 0xf100000
	s_addc_u32 s75, s63, 0
	s_add_u32 s74, s74, s0
	s_addc_u32 s75, s75, 0
	s_lshr_b32 s0, s36, 8
	s_lshl_b32 s0, s0, 11
	v_add_u32_e32 v224, s0, v227
	s_mov_b32 exec_lo, 0x10001
	s_mov_b32 exec_hi, 0x10001
	global_store_dwordx2 v224, v[132:133], s[74:75] offset:0 sc1
	global_store_dwordx2 v224, v[134:135], s[74:75] offset:256 sc1
	global_store_dwordx2 v224, v[136:137], s[74:75] offset:512 sc1
	global_store_dwordx2 v224, v[138:139], s[74:75] offset:768 sc1
	global_store_dwordx2 v224, v[232:233], s[74:75] offset:1024 sc1
	global_store_dwordx2 v224, v[234:235], s[74:75] offset:1280 sc1
	global_store_dwordx2 v224, v[236:237], s[74:75] offset:1536 sc1
	global_store_dwordx2 v224, v[150:151], s[74:75] offset:1792 sc1
	s_mov_b64 exec, -1
	s_waitcnt vmcnt(0)
	s_barrier
	v_readfirstlane_b32 s99, v0
	s_nop 3
	s_lshr_b32 s99, s99, 6
	s_cmp_lg_u32 s99, 0
	s_cbranch_scc0 .Lp6_signal
	s_mov_b32 s70, 0x0
	s_mov_b32 s71, 0
	v_lshl_add_u64 v[154:155], v[230:231], 0, s[70:71]
	global_store_dwordx4 v[154:155], v[98:101], off
	global_store_dwordx4 v[154:155], v[102:105], off offset:16
	s_mov_b32 s70, 0x20000
	s_mov_b32 s71, 0
	v_lshl_add_u64 v[156:157], v[230:231], 0, s[70:71]
	global_store_dwordx4 v[156:157], v[106:109], off
	global_store_dwordx4 v[156:157], v[110:113], off offset:16
	s_mov_b32 s70, 0x40000
	s_mov_b32 s71, 0
	v_lshl_add_u64 v[154:155], v[230:231], 0, s[70:71]
	global_store_dwordx4 v[154:155], v[114:117], off
	global_store_dwordx4 v[154:155], v[118:121], off offset:16
	s_mov_b32 s70, 0x60000
	s_mov_b32 s71, 0
	v_lshl_add_u64 v[156:157], v[230:231], 0, s[70:71]
	global_store_dwordx4 v[156:157], v[122:125], off
	global_store_dwordx4 v[156:157], v[126:129], off offset:16
	s_mov_b32 s70, 0x200
	s_mov_b32 s71, 0
	v_lshl_add_u64 v[154:155], v[230:231], 0, s[70:71]
	global_store_dwordx4 v[154:155], v[66:69], off
	global_store_dwordx4 v[154:155], v[70:73], off offset:16
	s_mov_b32 s70, 0x20200
	s_mov_b32 s71, 0
	v_lshl_add_u64 v[156:157], v[230:231], 0, s[70:71]
	global_store_dwordx4 v[156:157], v[74:77], off
	global_store_dwordx4 v[156:157], v[78:81], off offset:16
	s_mov_b32 s70, 0x40200
	s_mov_b32 s71, 0
	v_lshl_add_u64 v[154:155], v[230:231], 0, s[70:71]
	global_store_dwordx4 v[154:155], v[82:85], off
	global_store_dwordx4 v[154:155], v[86:89], off offset:16
	s_mov_b32 s70, 0x60200
	s_mov_b32 s71, 0
	v_lshl_add_u64 v[156:157], v[230:231], 0, s[70:71]
	global_store_dwordx4 v[156:157], v[90:93], off
	global_store_dwordx4 v[156:157], v[94:97], off offset:16
	s_branch .Lp6_wait_done

.Lp6_wait_done:
	s_barrier
	v_and_b32_e32 v246, 7, v0
	v_lshrrev_b32_e32 v247, 2, v246
	v_and_b32_e32 v246, 3, v246
	v_lshlrev_b32_e32 v247, 10, v247
	v_lshl_add_u32 v246, v246, 8, v247
	v_add_u32_e32 v246, v246, v227
	v_add_u32_e32 v247, 0x1000, v246
	global_load_dwordx2 v[238:239], v246, s[74:75] sc1
	global_load_dwordx2 v[240:241], v246, s[74:75] offset:2048 sc1
	global_load_dwordx2 v[242:243], v247, s[74:75] sc1
	global_load_dwordx2 v[244:245], v247, s[74:75] offset:2048 sc1
	v_readfirstlane_b32 s99, v0
	s_nop 3
	s_lshr_b32 s99, s99, 6
	s_cmp_lg_u32 s99, 0
	s_cbranch_scc1 .Lp6_w0done
	s_mov_b32 s70, 0x0
	s_mov_b32 s71, 0
	v_lshl_add_u64 v[154:155], v[230:231], 0, s[70:71]
	global_store_dwordx4 v[154:155], v[98:101], off
	global_store_dwordx4 v[154:155], v[102:105], off offset:16
	s_mov_b32 s70, 0x20000
	s_mov_b32 s71, 0
	v_lshl_add_u64 v[156:157], v[230:231], 0, s[70:71]
	global_store_dwordx4 v[156:157], v[106:109], off
	global_store_dwordx4 v[156:157], v[110:113], off offset:16
	s_mov_b32 s70, 0x40000
	s_mov_b32 s71, 0
	v_lshl_add_u64 v[154:155], v[230:231], 0, s[70:71]
	global_store_dwordx4 v[154:155], v[114:117], off
	global_store_dwordx4 v[154:155], v[118:121], off offset:16
	s_mov_b32 s70, 0x60000
	s_mov_b32 s71, 0
	v_lshl_add_u64 v[156:157], v[230:231], 0, s[70:71]
	global_store_dwordx4 v[156:157], v[122:125], off
	global_store_dwordx4 v[156:157], v[126:129], off offset:16
	s_mov_b32 s70, 0x200
	s_mov_b32 s71, 0
	v_lshl_add_u64 v[154:155], v[230:231], 0, s[70:71]
	global_store_dwordx4 v[154:155], v[66:69], off
	global_store_dwordx4 v[154:155], v[70:73], off offset:16
	s_mov_b32 s70, 0x20200
	s_mov_b32 s71, 0
	v_lshl_add_u64 v[156:157], v[230:231], 0, s[70:71]
	global_store_dwordx4 v[156:157], v[74:77], off
	global_store_dwordx4 v[156:157], v[78:81], off offset:16
	s_mov_b32 s70, 0x40200
	s_mov_b32 s71, 0
	v_lshl_add_u64 v[154:155], v[230:231], 0, s[70:71]
	global_store_dwordx4 v[154:155], v[82:85], off
	global_store_dwordx4 v[154:155], v[86:89], off offset:16
	s_mov_b32 s70, 0x60200
	s_mov_b32 s71, 0
	v_lshl_add_u64 v[156:157], v[230:231], 0, s[70:71]
	global_store_dwordx4 v[156:157], v[90:93], off
	global_store_dwordx4 v[156:157], v[94:97], off offset:16
	s_mov_b32 s70, 0x80000
	s_mov_b32 s71, 0
	v_lshl_add_u64 v[154:155], v[230:231], 0, s[70:71]
	global_store_dwordx4 v[154:155], v[34:37], off
	global_store_dwordx4 v[154:155], v[38:41], off offset:16
	s_mov_b32 s70, 0xa0000
	s_mov_b32 s71, 0
	v_lshl_add_u64 v[156:157], v[230:231], 0, s[70:71]
	global_store_dwordx4 v[156:157], v[42:45], off
	global_store_dwordx4 v[156:157], v[46:49], off offset:16
	s_mov_b32 s70, 0xc0000
	s_mov_b32 s71, 0
	v_lshl_add_u64 v[154:155], v[230:231], 0, s[70:71]
	global_store_dwordx4 v[154:155], v[50:53], off
	global_store_dwordx4 v[154:155], v[54:57], off offset:16
	s_mov_b32 s70, 0xe0000
	s_mov_b32 s71, 0
	v_lshl_add_u64 v[156:157], v[230:231], 0, s[70:71]
	global_store_dwordx4 v[156:157], v[58:61], off
	global_store_dwordx4 v[156:157], v[62:65], off offset:16
	s_mov_b32 s70, 0x80200
	s_mov_b32 s71, 0
	v_lshl_add_u64 v[154:155], v[230:231], 0, s[70:71]
	global_store_dwordx4 v[154:155], v[2:5], off
	global_store_dwordx4 v[154:155], v[6:9], off offset:16
	s_mov_b32 s70, 0xa0200
	s_mov_b32 s71, 0
	v_lshl_add_u64 v[156:157], v[230:231], 0, s[70:71]
	global_store_dwordx4 v[156:157], v[10:13], off
	global_store_dwordx4 v[156:157], v[14:17], off offset:16
	s_mov_b32 s70, 0xc0200
	s_mov_b32 s71, 0
	v_lshl_add_u64 v[154:155], v[230:231], 0, s[70:71]
	global_store_dwordx4 v[154:155], v[18:21], off
	global_store_dwordx4 v[154:155], v[22:25], off offset:16
	s_mov_b32 s70, 0xe0200
	s_mov_b32 s71, 0
	v_lshl_add_u64 v[156:157], v[230:231], 0, s[70:71]
	global_store_dwordx4 v[156:157], v[26:29], off
	global_store_dwordx4 v[156:157], v[30:33], off offset:16
	s_waitcnt vmcnt(32)
	s_branch .Lp6_comb
.Lp6_w0done:
	s_mov_b32 s70, 0x80000
	s_mov_b32 s71, 0
	v_lshl_add_u64 v[154:155], v[230:231], 0, s[70:71]
	global_store_dwordx4 v[154:155], v[34:37], off
	global_store_dwordx4 v[154:155], v[38:41], off offset:16
	s_mov_b32 s70, 0xa0000
	s_mov_b32 s71, 0
	v_lshl_add_u64 v[156:157], v[230:231], 0, s[70:71]
	global_store_dwordx4 v[156:157], v[42:45], off
	global_store_dwordx4 v[156:157], v[46:49], off offset:16
	s_mov_b32 s70, 0xc0000
	s_mov_b32 s71, 0
	v_lshl_add_u64 v[154:155], v[230:231], 0, s[70:71]
	global_store_dwordx4 v[154:155], v[50:53], off
	global_store_dwordx4 v[154:155], v[54:57], off offset:16
	s_mov_b32 s70, 0xe0000
	s_mov_b32 s71, 0
	v_lshl_add_u64 v[156:157], v[230:231], 0, s[70:71]
	global_store_dwordx4 v[156:157], v[58:61], off
	global_store_dwordx4 v[156:157], v[62:65], off offset:16
	s_mov_b32 s70, 0x80200
	s_mov_b32 s71, 0
	v_lshl_add_u64 v[154:155], v[230:231], 0, s[70:71]
	global_store_dwordx4 v[154:155], v[2:5], off
	global_store_dwordx4 v[154:155], v[6:9], off offset:16
	s_mov_b32 s70, 0xa0200
	s_mov_b32 s71, 0
	v_lshl_add_u64 v[156:157], v[230:231], 0, s[70:71]
	global_store_dwordx4 v[156:157], v[10:13], off
	global_store_dwordx4 v[156:157], v[14:17], off offset:16
	s_mov_b32 s70, 0xc0200
	s_mov_b32 s71, 0
	v_lshl_add_u64 v[154:155], v[230:231], 0, s[70:71]
	global_store_dwordx4 v[154:155], v[18:21], off
	global_store_dwordx4 v[154:155], v[22:25], off offset:16
	s_mov_b32 s70, 0xe0200
	s_mov_b32 s71, 0
	v_lshl_add_u64 v[156:157], v[230:231], 0, s[70:71]
	global_store_dwordx4 v[156:157], v[26:29], off
	global_store_dwordx4 v[156:157], v[30:33], off offset:16
	s_waitcnt vmcnt(16)
.Lp6_comb:
	v_mov_b32_e32 v248, 0x3727c5ac
	v_and_b32_e32 v249, 48, v0
	v_lshlrev_b32_e32 v249, 2, v249
	v_add_f32_e32 v250, v238, v240
	v_add_f32_e32 v246, v242, v244
	v_add_f32_e32 v250, v250, v246
	v_mul_f32_e32 v250, 0x3e800000, v250
	v_sub_f32_e32 v238, v238, v250
	v_sub_f32_e32 v240, v240, v250
	v_sub_f32_e32 v242, v242, v250
	v_sub_f32_e32 v244, v244, v250
	v_mul_f32_e32 v246, v238, v238
	v_fmac_f32_e32 v246, v240, v240
	v_fmac_f32_e32 v246, v242, v242
	v_fmac_f32_e32 v246, v244, v244
	v_add_f32_e32 v239, v239, v241
	v_add_f32_e32 v243, v243, v245
	v_add_f32_e32 v239, v239, v243
	v_fmamk_f32 v246, v246, 0x43800000, v239
	v_fmamk_f32 v246, v246, 0x3a800000, v248
	v_rsq_f32_e32 v251, v246
	s_nop 0
	v_add_u32_e32 v240, 0, v249
	ds_bpermute_b32 v132, v240, v250
	ds_bpermute_b32 v133, v240, v251
	v_add_u32_e32 v241, 4, v249
	ds_bpermute_b32 v134, v241, v250
	ds_bpermute_b32 v135, v241, v251
	v_add_u32_e32 v240, 8, v249
	ds_bpermute_b32 v136, v240, v250
	ds_bpermute_b32 v137, v240, v251
	v_add_u32_e32 v241, 12, v249
	ds_bpermute_b32 v138, v241, v250
	ds_bpermute_b32 v139, v241, v251
	v_add_u32_e32 v240, 16, v249
	ds_bpermute_b32 v232, v240, v250
	ds_bpermute_b32 v233, v240, v251
	v_add_u32_e32 v241, 20, v249
	ds_bpermute_b32 v234, v241, v250
	ds_bpermute_b32 v235, v241, v251
	v_add_u32_e32 v240, 24, v249
	ds_bpermute_b32 v236, v240, v250
	ds_bpermute_b32 v237, v240, v251
	v_add_u32_e32 v241, 28, v249
	ds_bpermute_b32 v150, v241, v250
	ds_bpermute_b32 v151, v241, v251
	s_waitcnt lgkmcnt(0)
	s_lshr_b32 s0, s36, 8
	s_cmp_lg_u32 s0, 0
	s_cbranch_scc1 .Lp6_nostats
	s_mov_b32 exec_lo, 0x10001
	s_mov_b32 exec_hi, 0x10001
	global_store_dwordx2 v227, v[132:133], s[44:45] offset:0
	global_store_dwordx2 v227, v[134:135], s[44:45] offset:256
	global_store_dwordx2 v227, v[136:137], s[44:45] offset:512
	global_store_dwordx2 v227, v[138:139], s[44:45] offset:768
	global_store_dwordx2 v227, v[232:233], s[44:45] offset:1024
	global_store_dwordx2 v227, v[234:235], s[44:45] offset:1280
	global_store_dwordx2 v227, v[236:237], s[44:45] offset:1536
	global_store_dwordx2 v227, v[150:151], s[44:45] offset:1792
	s_mov_b64 exec, -1

.LBB0_1460:
	v_lshlrev_b32_e32 v130, 3, v153
	v_and_b32_e32 v190, 0x78, v130
	v_ashrrev_i32_e32 v152, 4, v153
	v_lshrrev_b32_e32 v130, 1, v153
	v_and_b32_e32 v191, 0x60, v130
	v_or_b32_e32 v130, 4, v190
	v_lshlrev_b32_e32 v132, 2, v152
	v_bitop3_b32 v133, v132, v190, 48 bitop3:0x6c
	v_bitop3_b32 v132, v132, v130, 48 bitop3:0x6c
	v_lshlrev_b32_e32 v134, 9, v152
	v_lshlrev_b32_e32 v132, 2, v132
	v_add_u32_e32 v151, 32, v152
	v_lshlrev_b32_e32 v133, 2, v133
	v_add3_u32 v148, s64, v132, v134
	v_lshlrev_b32_e32 v132, 2, v151
	v_add3_u32 v147, s64, v133, v134
	v_bitop3_b32 v133, v132, v190, 48 bitop3:0x6c
	v_bitop3_b32 v132, v132, v130, 48 bitop3:0x6c
	v_lshlrev_b32_e32 v134, 9, v151
	v_lshlrev_b32_e32 v132, 2, v132
	v_add_u32_e32 v150, 64, v152
	v_lshlrev_b32_e32 v133, 2, v133
	v_add3_u32 v145, s64, v132, v134
	v_lshlrev_b32_e32 v132, 2, v150
	v_add3_u32 v146, s64, v133, v134
	v_bitop3_b32 v133, v132, v190, 48 bitop3:0x6c
	v_bitop3_b32 v132, v132, v130, 48 bitop3:0x6c
	v_lshlrev_b32_e32 v134, 9, v150
	v_lshlrev_b32_e32 v132, 2, v132
	v_add_u32_e32 v149, 0x60, v152
	v_lshlrev_b32_e32 v133, 2, v133
	v_add3_u32 v143, s64, v132, v134
	v_lshlrev_b32_e32 v132, 2, v149
	v_add3_u32 v144, s64, v133, v134
	v_bitop3_b32 v133, v132, v190, 48 bitop3:0x6c
	v_bitop3_b32 v130, v132, v130, 48 bitop3:0x6c
	v_lshlrev_b32_e32 v133, 2, v133
	v_lshlrev_b32_e32 v134, 9, v149
	v_lshlrev_b32_e32 v130, 2, v130
	s_lshl_b64 s[50:51], s[46:47], 2
	v_add3_u32 v141, s64, v133, v134
	v_add3_u32 v140, s64, v130, v134
	v_bfe_u32 v189, v153, 4, 2
	v_and_b32_e32 v188, 15, v153
	v_lshlrev_b32_e32 v193, 4, v189
	v_lshlrev_b32_e32 v153, 7, v153
	v_or_b32_e32 v192, v191, v188
	v_bitop3_b32 v188, v191, v193, v188 bitop3:0x36
	v_and_b32_e32 v153, 0xffff8000, v153
	v_lshlrev_b32_e32 v188, 2, v188
	v_lshl_or_b32 v189, v189, 11, v153
	v_add3_u32 v153, s64, v188, v189
	v_bitop3_b32 v149, v192, v193, 16 bitop3:0x36
	v_lshlrev_b32_e32 v149, 2, v149
	v_add3_u32 v149, s64, v149, v189
	v_lshrrev_b32_e32 v227, 4, v0
	v_add_u32_e32 v130, s73, v227
	v_lshlrev_b32_e32 v227, 3, v227
	v_and_b32_e32 v226, 15, v0
	v_lshlrev_b32_e32 v226, 5, v226
	s_lshl_b32 s0, s46, 2
	v_add_u32_e32 v226, s0, v226
	v_mov_b32_e32 v229, 0
	v_mov_b32_e32 v228, v130
	v_lshlrev_b64 v[228:229], 12, v[228:229]
	v_mov_b32_e32 v230, v226
	v_mov_b32_e32 v231, 0
	v_lshl_add_u64 v[228:229], v[228:229], 0, v[230:231]
	v_lshl_add_u64 v[230:231], s[66:67], 0, v[228:229]
	s_lshl_b32 s0, s73, 3
	s_add_u32 s52, s62, 0xf000000
	s_addc_u32 s53, s63, 0
	s_add_u32 s52, s52, s0
	s_addc_u32 s53, s53, 0
	v_readlane_b32 s70, v253, 8
	v_readlane_b32 s71, v253, 9
	v_readlane_b32 s74, v253, 10
	v_readlane_b32 s75, v253, 11
	s_mov_b32 s36, 0x20000
	s_mov_b32 s37, 0
	s_mov_b32 s39, 0
	s_nop 1
	s_mov_b32 s38, 0x0
	v_lshl_add_u64 v[150:151], v[230:231], 0, s[38:39]
	v_lshl_add_u64 v[220:221], v[150:151], 0, s[36:37]
	v_lshl_add_u64 v[222:223], v[220:221], 0, s[36:37]
	v_lshl_add_u64 v[224:225], v[222:223], 0, s[36:37]
	global_load_dwordx2 v[246:247], v227, s[52:53] offset:0
	global_load_dwordx2 v[248:249], v227, s[52:53] offset:256
	global_load_dwordx2 v[250:251], v227, s[52:53] offset:512
	global_load_dwordx2 v[218:219], v227, s[52:53] offset:768
	global_load_dwordx4 v[132:135], v226, s[70:71] offset:0
	global_load_dwordx4 v[136:139], v226, s[70:71] offset:16
	global_load_dwordx4 v[238:241], v226, s[74:75] offset:0
	global_load_dwordx4 v[242:245], v226, s[74:75] offset:16
	global_load_dwordx4 v[186:189], v[150:151], off
	global_load_dwordx4 v[190:193], v[150:151], off offset:16
	global_load_dwordx4 v[194:197], v[220:221], off
	global_load_dwordx4 v[198:201], v[220:221], off offset:16
	global_load_dwordx4 v[202:205], v[222:223], off
	global_load_dwordx4 v[206:209], v[222:223], off offset:16
	global_load_dwordx4 v[210:213], v[224:225], off
	global_load_dwordx4 v[214:217], v[224:225], off offset:16
	ds_write2st64_b32 v153, v126, v127 offset1:2
	ds_write2st64_b32 v153, v128, v129 offset0:4 offset1:6
	ds_write2st64_b32 v149, v98, v99 offset1:2
	ds_write2st64_b32 v149, v100, v101 offset0:4 offset1:6
	ds_write2st64_b32 v153, v102, v103 offset0:32 offset1:34
	ds_write2st64_b32 v153, v104, v105 offset0:36 offset1:38
	ds_write2st64_b32 v149, v106, v107 offset0:32 offset1:34
	ds_write2st64_b32 v149, v108, v109 offset0:36 offset1:38
	ds_write2st64_b32 v153, v110, v111 offset0:64 offset1:66
	ds_write2st64_b32 v153, v112, v113 offset0:68 offset1:70
	ds_write2st64_b32 v149, v114, v115 offset0:64 offset1:66
	ds_write2st64_b32 v149, v116, v117 offset0:68 offset1:70
	ds_write2st64_b32 v153, v118, v119 offset0:96 offset1:98
	ds_write2st64_b32 v153, v120, v121 offset0:100 offset1:102
	ds_write2st64_b32 v149, v122, v123 offset0:96 offset1:98
	ds_write2st64_b32 v149, v124, v125 offset0:100 offset1:102
	s_waitcnt lgkmcnt(0)
	s_barrier
	ds_read_b128 v[154:157], v147
	ds_read_b128 v[158:161], v148
	ds_read_b128 v[162:165], v146
	ds_read_b128 v[166:169], v145
	ds_read_b128 v[170:173], v144
	ds_read_b128 v[174:177], v143
	ds_read_b128 v[178:181], v141
	ds_read_b128 v[182:185], v140
	s_waitcnt vmcnt(0) lgkmcnt(0)
	s_barrier
	v_pk_add_f32 v[186:187], v[186:187], v[246:247] op_sel_hi:[1,0] neg_lo:[0,1] neg_hi:[0,1]
	v_pk_mul_f32 v[186:187], v[186:187], v[246:247] op_sel:[0,1]
	v_pk_fma_f32 v[186:187], v[132:133], v[186:187], v[238:239]
	v_pk_fma_f32 v[98:99], v[186:187], s[42:43], v[154:155] op_sel_hi:[1,0,1]
	v_pk_add_f32 v[188:189], v[188:189], v[246:247] op_sel_hi:[1,0] neg_lo:[0,1] neg_hi:[0,1]
	v_pk_mul_f32 v[188:189], v[188:189], v[246:247] op_sel:[0,1]
	v_pk_fma_f32 v[188:189], v[134:135], v[188:189], v[240:241]
	v_pk_fma_f32 v[100:101], v[188:189], s[42:43], v[156:157] op_sel_hi:[1,0,1]
	v_pk_add_f32 v[190:191], v[190:191], v[246:247] op_sel_hi:[1,0] neg_lo:[0,1] neg_hi:[0,1]
	v_pk_mul_f32 v[190:191], v[190:191], v[246:247] op_sel:[0,1]
	v_pk_fma_f32 v[190:191], v[136:137], v[190:191], v[242:243]
	v_pk_fma_f32 v[102:103], v[190:191], s[42:43], v[158:159] op_sel_hi:[1,0,1]
	v_pk_add_f32 v[192:193], v[192:193], v[246:247] op_sel_hi:[1,0] neg_lo:[0,1] neg_hi:[0,1]
	v_pk_mul_f32 v[192:193], v[192:193], v[246:247] op_sel:[0,1]
	v_pk_fma_f32 v[192:193], v[138:139], v[192:193], v[244:245]
	v_pk_fma_f32 v[104:105], v[192:193], s[42:43], v[160:161] op_sel_hi:[1,0,1]
	v_pk_add_f32 v[194:195], v[194:195], v[248:249] op_sel_hi:[1,0] neg_lo:[0,1] neg_hi:[0,1]
	v_pk_mul_f32 v[194:195], v[194:195], v[248:249] op_sel:[0,1]
	v_pk_fma_f32 v[194:195], v[132:133], v[194:195], v[238:239]
	v_pk_fma_f32 v[106:107], v[194:195], s[42:43], v[162:163] op_sel_hi:[1,0,1]
	v_pk_add_f32 v[196:197], v[196:197], v[248:249] op_sel_hi:[1,0] neg_lo:[0,1] neg_hi:[0,1]
	v_pk_mul_f32 v[196:197], v[196:197], v[248:249] op_sel:[0,1]
	v_pk_fma_f32 v[196:197], v[134:135], v[196:197], v[240:241]
	v_pk_fma_f32 v[108:109], v[196:197], s[42:43], v[164:165] op_sel_hi:[1,0,1]
	v_pk_add_f32 v[198:199], v[198:199], v[248:249] op_sel_hi:[1,0] neg_lo:[0,1] neg_hi:[0,1]
	v_pk_mul_f32 v[198:199], v[198:199], v[248:249] op_sel:[0,1]
	v_pk_fma_f32 v[198:199], v[136:137], v[198:199], v[242:243]
	v_pk_fma_f32 v[110:111], v[198:199], s[42:43], v[166:167] op_sel_hi:[1,0,1]
	v_pk_add_f32 v[200:201], v[200:201], v[248:249] op_sel_hi:[1,0] neg_lo:[0,1] neg_hi:[0,1]
	v_pk_mul_f32 v[200:201], v[200:201], v[248:249] op_sel:[0,1]
	v_pk_fma_f32 v[200:201], v[138:139], v[200:201], v[244:245]
	v_pk_fma_f32 v[112:113], v[200:201], s[42:43], v[168:169] op_sel_hi:[1,0,1]
	v_pk_add_f32 v[202:203], v[202:203], v[250:251] op_sel_hi:[1,0] neg_lo:[0,1] neg_hi:[0,1]
	v_pk_mul_f32 v[202:203], v[202:203], v[250:251] op_sel:[0,1]
	v_pk_fma_f32 v[202:203], v[132:133], v[202:203], v[238:239]
	v_pk_fma_f32 v[114:115], v[202:203], s[42:43], v[170:171] op_sel_hi:[1,0,1]
	v_pk_add_f32 v[204:205], v[204:205], v[250:251] op_sel_hi:[1,0] neg_lo:[0,1] neg_hi:[0,1]
	v_pk_mul_f32 v[204:205], v[204:205], v[250:251] op_sel:[0,1]
	v_pk_fma_f32 v[204:205], v[134:135], v[204:205], v[240:241]
	v_pk_fma_f32 v[116:117], v[204:205], s[42:43], v[172:173] op_sel_hi:[1,0,1]
	v_pk_add_f32 v[206:207], v[206:207], v[250:251] op_sel_hi:[1,0] neg_lo:[0,1] neg_hi:[0,1]
	v_pk_mul_f32 v[206:207], v[206:207], v[250:251] op_sel:[0,1]
	v_pk_fma_f32 v[206:207], v[136:137], v[206:207], v[242:243]
	v_pk_fma_f32 v[118:119], v[206:207], s[42:43], v[174:175] op_sel_hi:[1,0,1]
	v_pk_add_f32 v[208:209], v[208:209], v[250:251] op_sel_hi:[1,0] neg_lo:[0,1] neg_hi:[0,1]
	v_pk_mul_f32 v[208:209], v[208:209], v[250:251] op_sel:[0,1]
	v_pk_fma_f32 v[208:209], v[138:139], v[208:209], v[244:245]
	v_pk_fma_f32 v[120:121], v[208:209], s[42:43], v[176:177] op_sel_hi:[1,0,1]
	v_pk_add_f32 v[210:211], v[210:211], v[218:219] op_sel_hi:[1,0] neg_lo:[0,1] neg_hi:[0,1]
	v_pk_mul_f32 v[210:211], v[210:211], v[218:219] op_sel:[0,1]
	v_pk_fma_f32 v[210:211], v[132:133], v[210:211], v[238:239]
	v_pk_fma_f32 v[122:123], v[210:211], s[42:43], v[178:179] op_sel_hi:[1,0,1]
	v_pk_add_f32 v[212:213], v[212:213], v[218:219] op_sel_hi:[1,0] neg_lo:[0,1] neg_hi:[0,1]
	v_pk_mul_f32 v[212:213], v[212:213], v[218:219] op_sel:[0,1]
	v_pk_fma_f32 v[212:213], v[134:135], v[212:213], v[240:241]
	v_pk_fma_f32 v[124:125], v[212:213], s[42:43], v[180:181] op_sel_hi:[1,0,1]
	v_pk_add_f32 v[214:215], v[214:215], v[218:219] op_sel_hi:[1,0] neg_lo:[0,1] neg_hi:[0,1]
	v_pk_mul_f32 v[214:215], v[214:215], v[218:219] op_sel:[0,1]
	v_pk_fma_f32 v[214:215], v[136:137], v[214:215], v[242:243]
	v_pk_fma_f32 v[126:127], v[214:215], s[42:43], v[182:183] op_sel_hi:[1,0,1]
	v_pk_add_f32 v[216:217], v[216:217], v[218:219] op_sel_hi:[1,0] neg_lo:[0,1] neg_hi:[0,1]
	v_pk_mul_f32 v[216:217], v[216:217], v[218:219] op_sel:[0,1]
	v_pk_fma_f32 v[216:217], v[138:139], v[216:217], v[244:245]
	v_pk_fma_f32 v[128:129], v[216:217], s[42:43], v[184:185] op_sel_hi:[1,0,1]
	s_mov_b32 s38, 0x200
	v_lshl_add_u64 v[150:151], v[230:231], 0, s[38:39]
	v_lshl_add_u64 v[220:221], v[150:151], 0, s[36:37]
	v_lshl_add_u64 v[222:223], v[220:221], 0, s[36:37]
	v_lshl_add_u64 v[224:225], v[222:223], 0, s[36:37]
	global_load_dwordx2 v[246:247], v227, s[52:53] offset:0
	global_load_dwordx2 v[248:249], v227, s[52:53] offset:256
	global_load_dwordx2 v[250:251], v227, s[52:53] offset:512
	global_load_dwordx2 v[218:219], v227, s[52:53] offset:768
	global_load_dwordx4 v[132:135], v226, s[70:71] offset:512
	global_load_dwordx4 v[136:139], v226, s[70:71] offset:528
	global_load_dwordx4 v[238:241], v226, s[74:75] offset:512
	global_load_dwordx4 v[242:245], v226, s[74:75] offset:528
	global_load_dwordx4 v[186:189], v[150:151], off
	global_load_dwordx4 v[190:193], v[150:151], off offset:16
	global_load_dwordx4 v[194:197], v[220:221], off
	global_load_dwordx4 v[198:201], v[220:221], off offset:16
	global_load_dwordx4 v[202:205], v[222:223], off
	global_load_dwordx4 v[206:209], v[222:223], off offset:16
	global_load_dwordx4 v[210:213], v[224:225], off
	global_load_dwordx4 v[214:217], v[224:225], off offset:16
	ds_write2st64_b32 v153, v66, v67 offset1:2
	ds_write2st64_b32 v153, v68, v69 offset0:4 offset1:6
	ds_write2st64_b32 v149, v70, v71 offset1:2
	ds_write2st64_b32 v149, v72, v73 offset0:4 offset1:6
	ds_write2st64_b32 v153, v74, v75 offset0:32 offset1:34
	ds_write2st64_b32 v153, v76, v77 offset0:36 offset1:38
	ds_write2st64_b32 v149, v78, v79 offset0:32 offset1:34
	ds_write2st64_b32 v149, v80, v81 offset0:36 offset1:38
	ds_write2st64_b32 v153, v82, v83 offset0:64 offset1:66
	ds_write2st64_b32 v153, v84, v85 offset0:68 offset1:70
	ds_write2st64_b32 v149, v86, v87 offset0:64 offset1:66
	ds_write2st64_b32 v149, v88, v89 offset0:68 offset1:70
	ds_write2st64_b32 v153, v90, v91 offset0:96 offset1:98
	ds_write2st64_b32 v153, v92, v93 offset0:100 offset1:102
	ds_write2st64_b32 v149, v94, v95 offset0:96 offset1:98
	ds_write2st64_b32 v149, v96, v97 offset0:100 offset1:102
	s_waitcnt lgkmcnt(0)
	s_barrier
	ds_read_b128 v[154:157], v147
	ds_read_b128 v[158:161], v148
	ds_read_b128 v[162:165], v146
	ds_read_b128 v[166:169], v145
	ds_read_b128 v[170:173], v144
	ds_read_b128 v[174:177], v143
	ds_read_b128 v[178:181], v141
	ds_read_b128 v[182:185], v140
	s_waitcnt vmcnt(0) lgkmcnt(0)
	s_barrier
	v_pk_add_f32 v[186:187], v[186:187], v[246:247] op_sel_hi:[1,0] neg_lo:[0,1] neg_hi:[0,1]
	v_pk_mul_f32 v[186:187], v[186:187], v[246:247] op_sel:[0,1]
	v_pk_fma_f32 v[186:187], v[132:133], v[186:187], v[238:239]
	v_pk_fma_f32 v[66:67], v[186:187], s[42:43], v[154:155] op_sel_hi:[1,0,1]
	v_pk_add_f32 v[188:189], v[188:189], v[246:247] op_sel_hi:[1,0] neg_lo:[0,1] neg_hi:[0,1]
	v_pk_mul_f32 v[188:189], v[188:189], v[246:247] op_sel:[0,1]
	v_pk_fma_f32 v[188:189], v[134:135], v[188:189], v[240:241]
	v_pk_fma_f32 v[68:69], v[188:189], s[42:43], v[156:157] op_sel_hi:[1,0,1]
	v_pk_add_f32 v[190:191], v[190:191], v[246:247] op_sel_hi:[1,0] neg_lo:[0,1] neg_hi:[0,1]
	v_pk_mul_f32 v[190:191], v[190:191], v[246:247] op_sel:[0,1]
	v_pk_fma_f32 v[190:191], v[136:137], v[190:191], v[242:243]
	v_pk_fma_f32 v[70:71], v[190:191], s[42:43], v[158:159] op_sel_hi:[1,0,1]
	v_pk_add_f32 v[192:193], v[192:193], v[246:247] op_sel_hi:[1,0] neg_lo:[0,1] neg_hi:[0,1]
	v_pk_mul_f32 v[192:193], v[192:193], v[246:247] op_sel:[0,1]
	v_pk_fma_f32 v[192:193], v[138:139], v[192:193], v[244:245]
	v_pk_fma_f32 v[72:73], v[192:193], s[42:43], v[160:161] op_sel_hi:[1,0,1]
	v_pk_add_f32 v[194:195], v[194:195], v[248:249] op_sel_hi:[1,0] neg_lo:[0,1] neg_hi:[0,1]
	v_pk_mul_f32 v[194:195], v[194:195], v[248:249] op_sel:[0,1]
	v_pk_fma_f32 v[194:195], v[132:133], v[194:195], v[238:239]
	v_pk_fma_f32 v[74:75], v[194:195], s[42:43], v[162:163] op_sel_hi:[1,0,1]
	v_pk_add_f32 v[196:197], v[196:197], v[248:249] op_sel_hi:[1,0] neg_lo:[0,1] neg_hi:[0,1]
	v_pk_mul_f32 v[196:197], v[196:197], v[248:249] op_sel:[0,1]
	v_pk_fma_f32 v[196:197], v[134:135], v[196:197], v[240:241]
	v_pk_fma_f32 v[76:77], v[196:197], s[42:43], v[164:165] op_sel_hi:[1,0,1]
	v_pk_add_f32 v[198:199], v[198:199], v[248:249] op_sel_hi:[1,0] neg_lo:[0,1] neg_hi:[0,1]
	v_pk_mul_f32 v[198:199], v[198:199], v[248:249] op_sel:[0,1]
	v_pk_fma_f32 v[198:199], v[136:137], v[198:199], v[242:243]
	v_pk_fma_f32 v[78:79], v[198:199], s[42:43], v[166:167] op_sel_hi:[1,0,1]
	v_pk_add_f32 v[200:201], v[200:201], v[248:249] op_sel_hi:[1,0] neg_lo:[0,1] neg_hi:[0,1]
	v_pk_mul_f32 v[200:201], v[200:201], v[248:249] op_sel:[0,1]
	v_pk_fma_f32 v[200:201], v[138:139], v[200:201], v[244:245]
	v_pk_fma_f32 v[80:81], v[200:201], s[42:43], v[168:169] op_sel_hi:[1,0,1]
	v_pk_add_f32 v[202:203], v[202:203], v[250:251] op_sel_hi:[1,0] neg_lo:[0,1] neg_hi:[0,1]
	v_pk_mul_f32 v[202:203], v[202:203], v[250:251] op_sel:[0,1]
	v_pk_fma_f32 v[202:203], v[132:133], v[202:203], v[238:239]
	v_pk_fma_f32 v[82:83], v[202:203], s[42:43], v[170:171] op_sel_hi:[1,0,1]
	v_pk_add_f32 v[204:205], v[204:205], v[250:251] op_sel_hi:[1,0] neg_lo:[0,1] neg_hi:[0,1]
	v_pk_mul_f32 v[204:205], v[204:205], v[250:251] op_sel:[0,1]
	v_pk_fma_f32 v[204:205], v[134:135], v[204:205], v[240:241]
	v_pk_fma_f32 v[84:85], v[204:205], s[42:43], v[172:173] op_sel_hi:[1,0,1]
	v_pk_add_f32 v[206:207], v[206:207], v[250:251] op_sel_hi:[1,0] neg_lo:[0,1] neg_hi:[0,1]
	v_pk_mul_f32 v[206:207], v[206:207], v[250:251] op_sel:[0,1]
	v_pk_fma_f32 v[206:207], v[136:137], v[206:207], v[242:243]
	v_pk_fma_f32 v[86:87], v[206:207], s[42:43], v[174:175] op_sel_hi:[1,0,1]
	v_pk_add_f32 v[208:209], v[208:209], v[250:251] op_sel_hi:[1,0] neg_lo:[0,1] neg_hi:[0,1]
	v_pk_mul_f32 v[208:209], v[208:209], v[250:251] op_sel:[0,1]
	v_pk_fma_f32 v[208:209], v[138:139], v[208:209], v[244:245]
	v_pk_fma_f32 v[88:89], v[208:209], s[42:43], v[176:177] op_sel_hi:[1,0,1]
	v_pk_add_f32 v[210:211], v[210:211], v[218:219] op_sel_hi:[1,0] neg_lo:[0,1] neg_hi:[0,1]
	v_pk_mul_f32 v[210:211], v[210:211], v[218:219] op_sel:[0,1]
	v_pk_fma_f32 v[210:211], v[132:133], v[210:211], v[238:239]
	v_pk_fma_f32 v[90:91], v[210:211], s[42:43], v[178:179] op_sel_hi:[1,0,1]
	v_pk_add_f32 v[212:213], v[212:213], v[218:219] op_sel_hi:[1,0] neg_lo:[0,1] neg_hi:[0,1]
	v_pk_mul_f32 v[212:213], v[212:213], v[218:219] op_sel:[0,1]
	v_pk_fma_f32 v[212:213], v[134:135], v[212:213], v[240:241]
	v_pk_fma_f32 v[92:93], v[212:213], s[42:43], v[180:181] op_sel_hi:[1,0,1]
	v_pk_add_f32 v[214:215], v[214:215], v[218:219] op_sel_hi:[1,0] neg_lo:[0,1] neg_hi:[0,1]
	v_pk_mul_f32 v[214:215], v[214:215], v[218:219] op_sel:[0,1]
	v_pk_fma_f32 v[214:215], v[136:137], v[214:215], v[242:243]
	v_pk_fma_f32 v[94:95], v[214:215], s[42:43], v[182:183] op_sel_hi:[1,0,1]
	v_pk_add_f32 v[216:217], v[216:217], v[218:219] op_sel_hi:[1,0] neg_lo:[0,1] neg_hi:[0,1]
	v_pk_mul_f32 v[216:217], v[216:217], v[218:219] op_sel:[0,1]
	v_pk_fma_f32 v[216:217], v[138:139], v[216:217], v[244:245]
	v_pk_fma_f32 v[96:97], v[216:217], s[42:43], v[184:185] op_sel_hi:[1,0,1]
	s_mov_b32 s38, 0x80000
	v_lshl_add_u64 v[150:151], v[230:231], 0, s[38:39]
	v_lshl_add_u64 v[220:221], v[150:151], 0, s[36:37]
	v_lshl_add_u64 v[222:223], v[220:221], 0, s[36:37]
	v_lshl_add_u64 v[224:225], v[222:223], 0, s[36:37]
	global_load_dwordx2 v[246:247], v227, s[52:53] offset:1024
	global_load_dwordx2 v[248:249], v227, s[52:53] offset:1280
	global_load_dwordx2 v[250:251], v227, s[52:53] offset:1536
	global_load_dwordx2 v[218:219], v227, s[52:53] offset:1792
	global_load_dwordx4 v[132:135], v226, s[70:71] offset:0
	global_load_dwordx4 v[136:139], v226, s[70:71] offset:16
	global_load_dwordx4 v[238:241], v226, s[74:75] offset:0
	global_load_dwordx4 v[242:245], v226, s[74:75] offset:16
	global_load_dwordx4 v[186:189], v[150:151], off
	global_load_dwordx4 v[190:193], v[150:151], off offset:16
	global_load_dwordx4 v[194:197], v[220:221], off
	global_load_dwordx4 v[198:201], v[220:221], off offset:16
	global_load_dwordx4 v[202:205], v[222:223], off
	global_load_dwordx4 v[206:209], v[222:223], off offset:16
	global_load_dwordx4 v[210:213], v[224:225], off
	global_load_dwordx4 v[214:217], v[224:225], off offset:16
	ds_write2st64_b32 v153, v34, v35 offset1:2
	ds_write2st64_b32 v153, v36, v37 offset0:4 offset1:6
	ds_write2st64_b32 v149, v38, v39 offset1:2
	ds_write2st64_b32 v149, v40, v41 offset0:4 offset1:6
	ds_write2st64_b32 v153, v42, v43 offset0:32 offset1:34
	ds_write2st64_b32 v153, v44, v45 offset0:36 offset1:38
	ds_write2st64_b32 v149, v46, v47 offset0:32 offset1:34
	ds_write2st64_b32 v149, v48, v49 offset0:36 offset1:38
	ds_write2st64_b32 v153, v50, v51 offset0:64 offset1:66
	ds_write2st64_b32 v153, v52, v53 offset0:68 offset1:70
	ds_write2st64_b32 v149, v54, v55 offset0:64 offset1:66
	ds_write2st64_b32 v149, v56, v57 offset0:68 offset1:70
	ds_write2st64_b32 v153, v58, v59 offset0:96 offset1:98
	ds_write2st64_b32 v153, v60, v61 offset0:100 offset1:102
	ds_write2st64_b32 v149, v62, v63 offset0:96 offset1:98
	ds_write2st64_b32 v149, v64, v65 offset0:100 offset1:102
	s_waitcnt lgkmcnt(0)
	s_barrier
	ds_read_b128 v[154:157], v147
	ds_read_b128 v[158:161], v148
	ds_read_b128 v[162:165], v146
	ds_read_b128 v[166:169], v145
	ds_read_b128 v[170:173], v144
	ds_read_b128 v[174:177], v143
	ds_read_b128 v[178:181], v141
	ds_read_b128 v[182:185], v140
	s_waitcnt vmcnt(0) lgkmcnt(0)
	s_barrier
	v_pk_add_f32 v[186:187], v[186:187], v[246:247] op_sel_hi:[1,0] neg_lo:[0,1] neg_hi:[0,1]
	v_pk_mul_f32 v[186:187], v[186:187], v[246:247] op_sel:[0,1]
	v_pk_fma_f32 v[186:187], v[132:133], v[186:187], v[238:239]
	v_pk_fma_f32 v[34:35], v[186:187], s[42:43], v[154:155] op_sel_hi:[1,0,1]
	v_pk_add_f32 v[188:189], v[188:189], v[246:247] op_sel_hi:[1,0] neg_lo:[0,1] neg_hi:[0,1]
	v_pk_mul_f32 v[188:189], v[188:189], v[246:247] op_sel:[0,1]
	v_pk_fma_f32 v[188:189], v[134:135], v[188:189], v[240:241]
	v_pk_fma_f32 v[36:37], v[188:189], s[42:43], v[156:157] op_sel_hi:[1,0,1]
	v_pk_add_f32 v[190:191], v[190:191], v[246:247] op_sel_hi:[1,0] neg_lo:[0,1] neg_hi:[0,1]
	v_pk_mul_f32 v[190:191], v[190:191], v[246:247] op_sel:[0,1]
	v_pk_fma_f32 v[190:191], v[136:137], v[190:191], v[242:243]
	v_pk_fma_f32 v[38:39], v[190:191], s[42:43], v[158:159] op_sel_hi:[1,0,1]
	v_pk_add_f32 v[192:193], v[192:193], v[246:247] op_sel_hi:[1,0] neg_lo:[0,1] neg_hi:[0,1]
	v_pk_mul_f32 v[192:193], v[192:193], v[246:247] op_sel:[0,1]
	v_pk_fma_f32 v[192:193], v[138:139], v[192:193], v[244:245]
	v_pk_fma_f32 v[40:41], v[192:193], s[42:43], v[160:161] op_sel_hi:[1,0,1]
	v_pk_add_f32 v[194:195], v[194:195], v[248:249] op_sel_hi:[1,0] neg_lo:[0,1] neg_hi:[0,1]
	v_pk_mul_f32 v[194:195], v[194:195], v[248:249] op_sel:[0,1]
	v_pk_fma_f32 v[194:195], v[132:133], v[194:195], v[238:239]
	v_pk_fma_f32 v[42:43], v[194:195], s[42:43], v[162:163] op_sel_hi:[1,0,1]
	v_pk_add_f32 v[196:197], v[196:197], v[248:249] op_sel_hi:[1,0] neg_lo:[0,1] neg_hi:[0,1]
	v_pk_mul_f32 v[196:197], v[196:197], v[248:249] op_sel:[0,1]
	v_pk_fma_f32 v[196:197], v[134:135], v[196:197], v[240:241]
	v_pk_fma_f32 v[44:45], v[196:197], s[42:43], v[164:165] op_sel_hi:[1,0,1]
	v_pk_add_f32 v[198:199], v[198:199], v[248:249] op_sel_hi:[1,0] neg_lo:[0,1] neg_hi:[0,1]
	v_pk_mul_f32 v[198:199], v[198:199], v[248:249] op_sel:[0,1]
	v_pk_fma_f32 v[198:199], v[136:137], v[198:199], v[242:243]
	v_pk_fma_f32 v[46:47], v[198:199], s[42:43], v[166:167] op_sel_hi:[1,0,1]
	v_pk_add_f32 v[200:201], v[200:201], v[248:249] op_sel_hi:[1,0] neg_lo:[0,1] neg_hi:[0,1]
	v_pk_mul_f32 v[200:201], v[200:201], v[248:249] op_sel:[0,1]
	v_pk_fma_f32 v[200:201], v[138:139], v[200:201], v[244:245]
	v_pk_fma_f32 v[48:49], v[200:201], s[42:43], v[168:169] op_sel_hi:[1,0,1]
	v_pk_add_f32 v[202:203], v[202:203], v[250:251] op_sel_hi:[1,0] neg_lo:[0,1] neg_hi:[0,1]
	v_pk_mul_f32 v[202:203], v[202:203], v[250:251] op_sel:[0,1]
	v_pk_fma_f32 v[202:203], v[132:133], v[202:203], v[238:239]
	v_pk_fma_f32 v[50:51], v[202:203], s[42:43], v[170:171] op_sel_hi:[1,0,1]
	v_pk_add_f32 v[204:205], v[204:205], v[250:251] op_sel_hi:[1,0] neg_lo:[0,1] neg_hi:[0,1]
	v_pk_mul_f32 v[204:205], v[204:205], v[250:251] op_sel:[0,1]
	v_pk_fma_f32 v[204:205], v[134:135], v[204:205], v[240:241]
	v_pk_fma_f32 v[52:53], v[204:205], s[42:43], v[172:173] op_sel_hi:[1,0,1]
	v_pk_add_f32 v[206:207], v[206:207], v[250:251] op_sel_hi:[1,0] neg_lo:[0,1] neg_hi:[0,1]
	v_pk_mul_f32 v[206:207], v[206:207], v[250:251] op_sel:[0,1]
	v_pk_fma_f32 v[206:207], v[136:137], v[206:207], v[242:243]
	v_pk_fma_f32 v[54:55], v[206:207], s[42:43], v[174:175] op_sel_hi:[1,0,1]
	v_pk_add_f32 v[208:209], v[208:209], v[250:251] op_sel_hi:[1,0] neg_lo:[0,1] neg_hi:[0,1]
	v_pk_mul_f32 v[208:209], v[208:209], v[250:251] op_sel:[0,1]
	v_pk_fma_f32 v[208:209], v[138:139], v[208:209], v[244:245]
	v_pk_fma_f32 v[56:57], v[208:209], s[42:43], v[176:177] op_sel_hi:[1,0,1]
	v_pk_add_f32 v[210:211], v[210:211], v[218:219] op_sel_hi:[1,0] neg_lo:[0,1] neg_hi:[0,1]
	v_pk_mul_f32 v[210:211], v[210:211], v[218:219] op_sel:[0,1]
	v_pk_fma_f32 v[210:211], v[132:133], v[210:211], v[238:239]
	v_pk_fma_f32 v[58:59], v[210:211], s[42:43], v[178:179] op_sel_hi:[1,0,1]
	v_pk_add_f32 v[212:213], v[212:213], v[218:219] op_sel_hi:[1,0] neg_lo:[0,1] neg_hi:[0,1]
	v_pk_mul_f32 v[212:213], v[212:213], v[218:219] op_sel:[0,1]
	v_pk_fma_f32 v[212:213], v[134:135], v[212:213], v[240:241]
	v_pk_fma_f32 v[60:61], v[212:213], s[42:43], v[180:181] op_sel_hi:[1,0,1]
	v_pk_add_f32 v[214:215], v[214:215], v[218:219] op_sel_hi:[1,0] neg_lo:[0,1] neg_hi:[0,1]
	v_pk_mul_f32 v[214:215], v[214:215], v[218:219] op_sel:[0,1]
	v_pk_fma_f32 v[214:215], v[136:137], v[214:215], v[242:243]
	v_pk_fma_f32 v[62:63], v[214:215], s[42:43], v[182:183] op_sel_hi:[1,0,1]
	v_pk_add_f32 v[216:217], v[216:217], v[218:219] op_sel_hi:[1,0] neg_lo:[0,1] neg_hi:[0,1]
	v_pk_mul_f32 v[216:217], v[216:217], v[218:219] op_sel:[0,1]
	v_pk_fma_f32 v[216:217], v[138:139], v[216:217], v[244:245]
	v_pk_fma_f32 v[64:65], v[216:217], s[42:43], v[184:185] op_sel_hi:[1,0,1]
	s_mov_b32 s38, 0x80200
	v_lshl_add_u64 v[150:151], v[230:231], 0, s[38:39]
	v_lshl_add_u64 v[220:221], v[150:151], 0, s[36:37]
	v_lshl_add_u64 v[222:223], v[220:221], 0, s[36:37]
	v_lshl_add_u64 v[224:225], v[222:223], 0, s[36:37]
	global_load_dwordx2 v[246:247], v227, s[52:53] offset:1024
	global_load_dwordx2 v[248:249], v227, s[52:53] offset:1280
	global_load_dwordx2 v[250:251], v227, s[52:53] offset:1536
	global_load_dwordx2 v[218:219], v227, s[52:53] offset:1792
	global_load_dwordx4 v[132:135], v226, s[70:71] offset:512
	global_load_dwordx4 v[136:139], v226, s[70:71] offset:528
	global_load_dwordx4 v[238:241], v226, s[74:75] offset:512
	global_load_dwordx4 v[242:245], v226, s[74:75] offset:528
	global_load_dwordx4 v[186:189], v[150:151], off
	global_load_dwordx4 v[190:193], v[150:151], off offset:16
	global_load_dwordx4 v[194:197], v[220:221], off
	global_load_dwordx4 v[198:201], v[220:221], off offset:16
	global_load_dwordx4 v[202:205], v[222:223], off
	global_load_dwordx4 v[206:209], v[222:223], off offset:16
	global_load_dwordx4 v[210:213], v[224:225], off
	global_load_dwordx4 v[214:217], v[224:225], off offset:16
	ds_write2st64_b32 v153, v2, v3 offset1:2
	ds_write2st64_b32 v153, v4, v5 offset0:4 offset1:6
	ds_write2st64_b32 v149, v6, v7 offset1:2
	ds_write2st64_b32 v149, v8, v9 offset0:4 offset1:6
	ds_write2st64_b32 v153, v10, v11 offset0:32 offset1:34
	ds_write2st64_b32 v153, v12, v13 offset0:36 offset1:38
	ds_write2st64_b32 v149, v14, v15 offset0:32 offset1:34
	ds_write2st64_b32 v149, v16, v17 offset0:36 offset1:38
	ds_write2st64_b32 v153, v18, v19 offset0:64 offset1:66
	ds_write2st64_b32 v153, v20, v21 offset0:68 offset1:70
	ds_write2st64_b32 v149, v22, v23 offset0:64 offset1:66
	ds_write2st64_b32 v149, v24, v25 offset0:68 offset1:70
	ds_write2st64_b32 v153, v26, v27 offset0:96 offset1:98
	ds_write2st64_b32 v153, v28, v29 offset0:100 offset1:102
	ds_write2st64_b32 v149, v30, v31 offset0:96 offset1:98
	ds_write2st64_b32 v149, v32, v33 offset0:100 offset1:102
	s_waitcnt lgkmcnt(0)
	s_barrier
	ds_read_b128 v[154:157], v147
	ds_read_b128 v[158:161], v148
	ds_read_b128 v[162:165], v146
	ds_read_b128 v[166:169], v145
	ds_read_b128 v[170:173], v144
	ds_read_b128 v[174:177], v143
	ds_read_b128 v[178:181], v141
	ds_read_b128 v[182:185], v140
	s_waitcnt vmcnt(0) lgkmcnt(0)
	v_pk_add_f32 v[186:187], v[186:187], v[246:247] op_sel_hi:[1,0] neg_lo:[0,1] neg_hi:[0,1]
	v_pk_mul_f32 v[186:187], v[186:187], v[246:247] op_sel:[0,1]
	v_pk_fma_f32 v[186:187], v[132:133], v[186:187], v[238:239]
	v_pk_fma_f32 v[2:3], v[186:187], s[42:43], v[154:155] op_sel_hi:[1,0,1]
	v_pk_add_f32 v[188:189], v[188:189], v[246:247] op_sel_hi:[1,0] neg_lo:[0,1] neg_hi:[0,1]
	v_pk_mul_f32 v[188:189], v[188:189], v[246:247] op_sel:[0,1]
	v_pk_fma_f32 v[188:189], v[134:135], v[188:189], v[240:241]
	v_pk_fma_f32 v[4:5], v[188:189], s[42:43], v[156:157] op_sel_hi:[1,0,1]
	v_pk_add_f32 v[190:191], v[190:191], v[246:247] op_sel_hi:[1,0] neg_lo:[0,1] neg_hi:[0,1]
	v_pk_mul_f32 v[190:191], v[190:191], v[246:247] op_sel:[0,1]
	v_pk_fma_f32 v[190:191], v[136:137], v[190:191], v[242:243]
	v_pk_fma_f32 v[6:7], v[190:191], s[42:43], v[158:159] op_sel_hi:[1,0,1]
	v_pk_add_f32 v[192:193], v[192:193], v[246:247] op_sel_hi:[1,0] neg_lo:[0,1] neg_hi:[0,1]
	v_pk_mul_f32 v[192:193], v[192:193], v[246:247] op_sel:[0,1]
	v_pk_fma_f32 v[192:193], v[138:139], v[192:193], v[244:245]
	v_pk_fma_f32 v[8:9], v[192:193], s[42:43], v[160:161] op_sel_hi:[1,0,1]
	v_pk_add_f32 v[194:195], v[194:195], v[248:249] op_sel_hi:[1,0] neg_lo:[0,1] neg_hi:[0,1]
	v_pk_mul_f32 v[194:195], v[194:195], v[248:249] op_sel:[0,1]
	v_pk_fma_f32 v[194:195], v[132:133], v[194:195], v[238:239]
	v_pk_fma_f32 v[10:11], v[194:195], s[42:43], v[162:163] op_sel_hi:[1,0,1]
	v_pk_add_f32 v[196:197], v[196:197], v[248:249] op_sel_hi:[1,0] neg_lo:[0,1] neg_hi:[0,1]
	v_pk_mul_f32 v[196:197], v[196:197], v[248:249] op_sel:[0,1]
	v_pk_fma_f32 v[196:197], v[134:135], v[196:197], v[240:241]
	v_pk_fma_f32 v[12:13], v[196:197], s[42:43], v[164:165] op_sel_hi:[1,0,1]
	v_pk_add_f32 v[198:199], v[198:199], v[248:249] op_sel_hi:[1,0] neg_lo:[0,1] neg_hi:[0,1]
	v_pk_mul_f32 v[198:199], v[198:199], v[248:249] op_sel:[0,1]
	v_pk_fma_f32 v[198:199], v[136:137], v[198:199], v[242:243]
	v_pk_fma_f32 v[14:15], v[198:199], s[42:43], v[166:167] op_sel_hi:[1,0,1]
	v_pk_add_f32 v[200:201], v[200:201], v[248:249] op_sel_hi:[1,0] neg_lo:[0,1] neg_hi:[0,1]
	v_pk_mul_f32 v[200:201], v[200:201], v[248:249] op_sel:[0,1]
	v_pk_fma_f32 v[200:201], v[138:139], v[200:201], v[244:245]
	v_pk_fma_f32 v[16:17], v[200:201], s[42:43], v[168:169] op_sel_hi:[1,0,1]
	v_pk_add_f32 v[202:203], v[202:203], v[250:251] op_sel_hi:[1,0] neg_lo:[0,1] neg_hi:[0,1]
	v_pk_mul_f32 v[202:203], v[202:203], v[250:251] op_sel:[0,1]
	v_pk_fma_f32 v[202:203], v[132:133], v[202:203], v[238:239]
	v_pk_fma_f32 v[18:19], v[202:203], s[42:43], v[170:171] op_sel_hi:[1,0,1]
	v_pk_add_f32 v[204:205], v[204:205], v[250:251] op_sel_hi:[1,0] neg_lo:[0,1] neg_hi:[0,1]
	v_pk_mul_f32 v[204:205], v[204:205], v[250:251] op_sel:[0,1]
	v_pk_fma_f32 v[204:205], v[134:135], v[204:205], v[240:241]
	v_pk_fma_f32 v[20:21], v[204:205], s[42:43], v[172:173] op_sel_hi:[1,0,1]
	v_pk_add_f32 v[206:207], v[206:207], v[250:251] op_sel_hi:[1,0] neg_lo:[0,1] neg_hi:[0,1]
	v_pk_mul_f32 v[206:207], v[206:207], v[250:251] op_sel:[0,1]
	v_pk_fma_f32 v[206:207], v[136:137], v[206:207], v[242:243]
	v_pk_fma_f32 v[22:23], v[206:207], s[42:43], v[174:175] op_sel_hi:[1,0,1]
	v_pk_add_f32 v[208:209], v[208:209], v[250:251] op_sel_hi:[1,0] neg_lo:[0,1] neg_hi:[0,1]
	v_pk_mul_f32 v[208:209], v[208:209], v[250:251] op_sel:[0,1]
	v_pk_fma_f32 v[208:209], v[138:139], v[208:209], v[244:245]
	v_pk_fma_f32 v[24:25], v[208:209], s[42:43], v[176:177] op_sel_hi:[1,0,1]
	v_pk_add_f32 v[210:211], v[210:211], v[218:219] op_sel_hi:[1,0] neg_lo:[0,1] neg_hi:[0,1]
	v_pk_mul_f32 v[210:211], v[210:211], v[218:219] op_sel:[0,1]
	v_pk_fma_f32 v[210:211], v[132:133], v[210:211], v[238:239]
	v_pk_fma_f32 v[26:27], v[210:211], s[42:43], v[178:179] op_sel_hi:[1,0,1]
	v_pk_add_f32 v[212:213], v[212:213], v[218:219] op_sel_hi:[1,0] neg_lo:[0,1] neg_hi:[0,1]
	v_pk_mul_f32 v[212:213], v[212:213], v[218:219] op_sel:[0,1]
	v_pk_fma_f32 v[212:213], v[134:135], v[212:213], v[240:241]
	v_pk_fma_f32 v[28:29], v[212:213], s[42:43], v[180:181] op_sel_hi:[1,0,1]
	v_pk_add_f32 v[214:215], v[214:215], v[218:219] op_sel_hi:[1,0] neg_lo:[0,1] neg_hi:[0,1]
	v_pk_mul_f32 v[214:215], v[214:215], v[218:219] op_sel:[0,1]
	v_pk_fma_f32 v[214:215], v[136:137], v[214:215], v[242:243]
	v_pk_fma_f32 v[30:31], v[214:215], s[42:43], v[182:183] op_sel_hi:[1,0,1]
	v_pk_add_f32 v[216:217], v[216:217], v[218:219] op_sel_hi:[1,0] neg_lo:[0,1] neg_hi:[0,1]
	v_pk_mul_f32 v[216:217], v[216:217], v[218:219] op_sel:[0,1]
	v_pk_fma_f32 v[216:217], v[138:139], v[216:217], v[244:245]
	v_pk_fma_f32 v[32:33], v[216:217], s[42:43], v[184:185] op_sel_hi:[1,0,1]
	v_readlane_b32 s70, v253, 18
	v_readlane_b32 s71, v253, 19
	v_readlane_b32 s74, v253, 20
	v_readlane_b32 s75, v253, 21
	v_lshrrev_b64 v[222:223], 1, v[228:229]
	v_lshl_add_u64 v[222:223], s[60:61], 0, v[222:223]
	s_nop 2
	global_load_dwordx4 v[186:189], v226, s[70:71] offset:0
	global_load_dwordx4 v[190:193], v226, s[70:71] offset:16
	global_load_dwordx4 v[194:197], v226, s[70:71] offset:512
	global_load_dwordx4 v[198:201], v226, s[70:71] offset:528
	global_load_dwordx4 v[202:205], v226, s[74:75] offset:0
	global_load_dwordx4 v[206:209], v226, s[74:75] offset:16
	global_load_dwordx4 v[210:213], v226, s[74:75] offset:512
	global_load_dwordx4 v[214:217], v226, s[74:75] offset:528
	v_pk_add_f32 v[154:155], v[98:99], v[100:101]
	v_pk_add_f32 v[156:157], v[106:107], v[108:109]
	v_pk_add_f32 v[158:159], v[114:115], v[116:117]
	v_pk_add_f32 v[160:161], v[122:123], v[124:125]
	v_pk_add_f32 v[162:163], v[34:35], v[36:37]
	v_pk_add_f32 v[164:165], v[42:43], v[44:45]
	v_pk_add_f32 v[166:167], v[50:51], v[52:53]
	v_pk_add_f32 v[168:169], v[58:59], v[60:61]
	v_pk_add_f32 v[154:155], v[154:155], v[102:103]
	v_pk_add_f32 v[156:157], v[156:157], v[110:111]
	v_pk_add_f32 v[158:159], v[158:159], v[118:119]
	v_pk_add_f32 v[160:161], v[160:161], v[126:127]
	v_pk_add_f32 v[162:163], v[162:163], v[38:39]
	v_pk_add_f32 v[164:165], v[164:165], v[46:47]
	v_pk_add_f32 v[166:167], v[166:167], v[54:55]
	v_pk_add_f32 v[168:169], v[168:169], v[62:63]
	v_pk_add_f32 v[154:155], v[154:155], v[104:105]
	v_pk_add_f32 v[156:157], v[156:157], v[112:113]
	v_pk_add_f32 v[158:159], v[158:159], v[120:121]
	v_pk_add_f32 v[160:161], v[160:161], v[128:129]
	v_pk_add_f32 v[162:163], v[162:163], v[40:41]
	v_pk_add_f32 v[164:165], v[164:165], v[48:49]
	v_pk_add_f32 v[166:167], v[166:167], v[56:57]
	v_pk_add_f32 v[168:169], v[168:169], v[64:65]
	v_pk_add_f32 v[154:155], v[154:155], v[66:67]
	v_pk_add_f32 v[156:157], v[156:157], v[74:75]
	v_pk_add_f32 v[158:159], v[158:159], v[82:83]
	v_pk_add_f32 v[160:161], v[160:161], v[90:91]
	v_pk_add_f32 v[162:163], v[162:163], v[2:3]
	v_pk_add_f32 v[164:165], v[164:165], v[10:11]
	v_pk_add_f32 v[166:167], v[166:167], v[18:19]
	v_pk_add_f32 v[168:169], v[168:169], v[26:27]
	v_pk_add_f32 v[154:155], v[154:155], v[68:69]
	v_pk_add_f32 v[156:157], v[156:157], v[76:77]
	v_pk_add_f32 v[158:159], v[158:159], v[84:85]
	v_pk_add_f32 v[160:161], v[160:161], v[92:93]
	v_pk_add_f32 v[162:163], v[162:163], v[4:5]
	v_pk_add_f32 v[164:165], v[164:165], v[12:13]
	v_pk_add_f32 v[166:167], v[166:167], v[20:21]
	v_pk_add_f32 v[168:169], v[168:169], v[28:29]
	v_pk_add_f32 v[154:155], v[154:155], v[70:71]
	v_pk_add_f32 v[156:157], v[156:157], v[78:79]
	v_pk_add_f32 v[158:159], v[158:159], v[86:87]
	v_pk_add_f32 v[160:161], v[160:161], v[94:95]
	v_pk_add_f32 v[162:163], v[162:163], v[6:7]
	v_pk_add_f32 v[164:165], v[164:165], v[14:15]
	v_pk_add_f32 v[166:167], v[166:167], v[22:23]
	v_pk_add_f32 v[168:169], v[168:169], v[30:31]
	v_pk_add_f32 v[154:155], v[154:155], v[72:73]
	v_pk_add_f32 v[156:157], v[156:157], v[80:81]
	v_pk_add_f32 v[158:159], v[158:159], v[88:89]
	v_pk_add_f32 v[160:161], v[160:161], v[96:97]
	v_pk_add_f32 v[162:163], v[162:163], v[8:9]
	v_pk_add_f32 v[164:165], v[164:165], v[16:17]
	v_pk_add_f32 v[166:167], v[166:167], v[24:25]
	v_pk_add_f32 v[168:169], v[168:169], v[32:33]
	v_add_f32_e32 v132, v154, v155
	v_add_f32_e32 v134, v156, v157
	v_add_f32_e32 v136, v158, v159
	v_add_f32_e32 v138, v160, v161
	v_add_f32_e32 v232, v162, v163
	v_add_f32_e32 v234, v164, v165
	v_add_f32_e32 v236, v166, v167
	v_add_f32_e32 v150, v168, v169
	v_add_f32_dpp v132, v132, v132 quad_perm:[1,0,3,2] row_mask:0xf bank_mask:0xf
	v_add_f32_dpp v134, v134, v134 quad_perm:[1,0,3,2] row_mask:0xf bank_mask:0xf
	v_add_f32_dpp v136, v136, v136 quad_perm:[1,0,3,2] row_mask:0xf bank_mask:0xf
	v_add_f32_dpp v138, v138, v138 quad_perm:[1,0,3,2] row_mask:0xf bank_mask:0xf
	v_add_f32_dpp v232, v232, v232 quad_perm:[1,0,3,2] row_mask:0xf bank_mask:0xf
	v_add_f32_dpp v234, v234, v234 quad_perm:[1,0,3,2] row_mask:0xf bank_mask:0xf
	v_add_f32_dpp v236, v236, v236 quad_perm:[1,0,3,2] row_mask:0xf bank_mask:0xf
	v_add_f32_dpp v150, v150, v150 quad_perm:[1,0,3,2] row_mask:0xf bank_mask:0xf
	v_add_f32_dpp v132, v132, v132 quad_perm:[2,3,0,1] row_mask:0xf bank_mask:0xf
	v_add_f32_dpp v134, v134, v134 quad_perm:[2,3,0,1] row_mask:0xf bank_mask:0xf
	v_add_f32_dpp v136, v136, v136 quad_perm:[2,3,0,1] row_mask:0xf bank_mask:0xf
	v_add_f32_dpp v138, v138, v138 quad_perm:[2,3,0,1] row_mask:0xf bank_mask:0xf
	v_add_f32_dpp v232, v232, v232 quad_perm:[2,3,0,1] row_mask:0xf bank_mask:0xf
	v_add_f32_dpp v234, v234, v234 quad_perm:[2,3,0,1] row_mask:0xf bank_mask:0xf
	v_add_f32_dpp v236, v236, v236 quad_perm:[2,3,0,1] row_mask:0xf bank_mask:0xf
	v_add_f32_dpp v150, v150, v150 quad_perm:[2,3,0,1] row_mask:0xf bank_mask:0xf
	v_add_f32_dpp v132, v132, v132 row_half_mirror row_mask:0xf bank_mask:0xf
	v_add_f32_dpp v134, v134, v134 row_half_mirror row_mask:0xf bank_mask:0xf
	v_add_f32_dpp v136, v136, v136 row_half_mirror row_mask:0xf bank_mask:0xf
	v_add_f32_dpp v138, v138, v138 row_half_mirror row_mask:0xf bank_mask:0xf
	v_add_f32_dpp v232, v232, v232 row_half_mirror row_mask:0xf bank_mask:0xf
	v_add_f32_dpp v234, v234, v234 row_half_mirror row_mask:0xf bank_mask:0xf
	v_add_f32_dpp v236, v236, v236 row_half_mirror row_mask:0xf bank_mask:0xf
	v_add_f32_dpp v150, v150, v150 row_half_mirror row_mask:0xf bank_mask:0xf
	v_add_f32_dpp v132, v132, v132 row_mirror row_mask:0xf bank_mask:0xf
	v_add_f32_dpp v134, v134, v134 row_mirror row_mask:0xf bank_mask:0xf
	v_add_f32_dpp v136, v136, v136 row_mirror row_mask:0xf bank_mask:0xf
	v_add_f32_dpp v138, v138, v138 row_mirror row_mask:0xf bank_mask:0xf
	v_add_f32_dpp v232, v232, v232 row_mirror row_mask:0xf bank_mask:0xf
	v_add_f32_dpp v234, v234, v234 row_mirror row_mask:0xf bank_mask:0xf
	v_add_f32_dpp v236, v236, v236 row_mirror row_mask:0xf bank_mask:0xf
	v_add_f32_dpp v150, v150, v150 row_mirror row_mask:0xf bank_mask:0xf
	v_mul_f32_e32 v132, 0x3b800000, v132
	v_mul_f32_e32 v134, 0x3b800000, v134
	v_mul_f32_e32 v136, 0x3b800000, v136
	v_mul_f32_e32 v138, 0x3b800000, v138
	v_mul_f32_e32 v232, 0x3b800000, v232
	v_mul_f32_e32 v234, 0x3b800000, v234
	v_mul_f32_e32 v236, 0x3b800000, v236
	v_mul_f32_e32 v150, 0x3b800000, v150
	v_pk_add_f32 v[218:219], v[98:99], v[132:133] op_sel_hi:[1,0] neg_lo:[0,1] neg_hi:[0,1]
	v_pk_mul_f32 v[170:171], v[218:219], v[218:219]
	v_pk_add_f32 v[220:221], v[106:107], v[134:135] op_sel_hi:[1,0] neg_lo:[0,1] neg_hi:[0,1]
	v_pk_mul_f32 v[172:173], v[220:221], v[220:221]
	v_pk_add_f32 v[218:219], v[114:115], v[136:137] op_sel_hi:[1,0] neg_lo:[0,1] neg_hi:[0,1]
	v_pk_mul_f32 v[174:175], v[218:219], v[218:219]
	v_pk_add_f32 v[220:221], v[122:123], v[138:139] op_sel_hi:[1,0] neg_lo:[0,1] neg_hi:[0,1]
	v_pk_mul_f32 v[176:177], v[220:221], v[220:221]
	v_pk_add_f32 v[218:219], v[34:35], v[232:233] op_sel_hi:[1,0] neg_lo:[0,1] neg_hi:[0,1]
	v_pk_mul_f32 v[178:179], v[218:219], v[218:219]
	v_pk_add_f32 v[220:221], v[42:43], v[234:235] op_sel_hi:[1,0] neg_lo:[0,1] neg_hi:[0,1]
	v_pk_mul_f32 v[180:181], v[220:221], v[220:221]
	v_pk_add_f32 v[218:219], v[50:51], v[236:237] op_sel_hi:[1,0] neg_lo:[0,1] neg_hi:[0,1]
	v_pk_mul_f32 v[182:183], v[218:219], v[218:219]
	v_pk_add_f32 v[220:221], v[58:59], v[150:151] op_sel_hi:[1,0] neg_lo:[0,1] neg_hi:[0,1]
	v_pk_mul_f32 v[184:185], v[220:221], v[220:221]
	v_pk_add_f32 v[218:219], v[100:101], v[132:133] op_sel_hi:[1,0] neg_lo:[0,1] neg_hi:[0,1]
	v_pk_fma_f32 v[170:171], v[218:219], v[218:219], v[170:171]
	v_pk_add_f32 v[220:221], v[108:109], v[134:135] op_sel_hi:[1,0] neg_lo:[0,1] neg_hi:[0,1]
	v_pk_fma_f32 v[172:173], v[220:221], v[220:221], v[172:173]
	v_pk_add_f32 v[218:219], v[116:117], v[136:137] op_sel_hi:[1,0] neg_lo:[0,1] neg_hi:[0,1]
	v_pk_fma_f32 v[174:175], v[218:219], v[218:219], v[174:175]
	v_pk_add_f32 v[220:221], v[124:125], v[138:139] op_sel_hi:[1,0] neg_lo:[0,1] neg_hi:[0,1]
	v_pk_fma_f32 v[176:177], v[220:221], v[220:221], v[176:177]
	v_pk_add_f32 v[218:219], v[36:37], v[232:233] op_sel_hi:[1,0] neg_lo:[0,1] neg_hi:[0,1]
	v_pk_fma_f32 v[178:179], v[218:219], v[218:219], v[178:179]
	v_pk_add_f32 v[220:221], v[44:45], v[234:235] op_sel_hi:[1,0] neg_lo:[0,1] neg_hi:[0,1]
	v_pk_fma_f32 v[180:181], v[220:221], v[220:221], v[180:181]
	v_pk_add_f32 v[218:219], v[52:53], v[236:237] op_sel_hi:[1,0] neg_lo:[0,1] neg_hi:[0,1]
	v_pk_fma_f32 v[182:183], v[218:219], v[218:219], v[182:183]
	v_pk_add_f32 v[220:221], v[60:61], v[150:151] op_sel_hi:[1,0] neg_lo:[0,1] neg_hi:[0,1]
	v_pk_fma_f32 v[184:185], v[220:221], v[220:221], v[184:185]
	v_pk_add_f32 v[218:219], v[102:103], v[132:133] op_sel_hi:[1,0] neg_lo:[0,1] neg_hi:[0,1]
	v_pk_fma_f32 v[170:171], v[218:219], v[218:219], v[170:171]
	v_pk_add_f32 v[220:221], v[110:111], v[134:135] op_sel_hi:[1,0] neg_lo:[0,1] neg_hi:[0,1]
	v_pk_fma_f32 v[172:173], v[220:221], v[220:221], v[172:173]
	v_pk_add_f32 v[218:219], v[118:119], v[136:137] op_sel_hi:[1,0] neg_lo:[0,1] neg_hi:[0,1]
	v_pk_fma_f32 v[174:175], v[218:219], v[218:219], v[174:175]
	v_pk_add_f32 v[220:221], v[126:127], v[138:139] op_sel_hi:[1,0] neg_lo:[0,1] neg_hi:[0,1]
	v_pk_fma_f32 v[176:177], v[220:221], v[220:221], v[176:177]
	v_pk_add_f32 v[218:219], v[38:39], v[232:233] op_sel_hi:[1,0] neg_lo:[0,1] neg_hi:[0,1]
	v_pk_fma_f32 v[178:179], v[218:219], v[218:219], v[178:179]
	v_pk_add_f32 v[220:221], v[46:47], v[234:235] op_sel_hi:[1,0] neg_lo:[0,1] neg_hi:[0,1]
	v_pk_fma_f32 v[180:181], v[220:221], v[220:221], v[180:181]
	v_pk_add_f32 v[218:219], v[54:55], v[236:237] op_sel_hi:[1,0] neg_lo:[0,1] neg_hi:[0,1]
	v_pk_fma_f32 v[182:183], v[218:219], v[218:219], v[182:183]
	v_pk_add_f32 v[220:221], v[62:63], v[150:151] op_sel_hi:[1,0] neg_lo:[0,1] neg_hi:[0,1]
	v_pk_fma_f32 v[184:185], v[220:221], v[220:221], v[184:185]
	v_pk_add_f32 v[218:219], v[104:105], v[132:133] op_sel_hi:[1,0] neg_lo:[0,1] neg_hi:[0,1]
	v_pk_fma_f32 v[170:171], v[218:219], v[218:219], v[170:171]
	v_pk_add_f32 v[220:221], v[112:113], v[134:135] op_sel_hi:[1,0] neg_lo:[0,1] neg_hi:[0,1]
	v_pk_fma_f32 v[172:173], v[220:221], v[220:221], v[172:173]
	v_pk_add_f32 v[218:219], v[120:121], v[136:137] op_sel_hi:[1,0] neg_lo:[0,1] neg_hi:[0,1]
	v_pk_fma_f32 v[174:175], v[218:219], v[218:219], v[174:175]
	v_pk_add_f32 v[220:221], v[128:129], v[138:139] op_sel_hi:[1,0] neg_lo:[0,1] neg_hi:[0,1]
	v_pk_fma_f32 v[176:177], v[220:221], v[220:221], v[176:177]
	v_pk_add_f32 v[218:219], v[40:41], v[232:233] op_sel_hi:[1,0] neg_lo:[0,1] neg_hi:[0,1]
	v_pk_fma_f32 v[178:179], v[218:219], v[218:219], v[178:179]
	v_pk_add_f32 v[220:221], v[48:49], v[234:235] op_sel_hi:[1,0] neg_lo:[0,1] neg_hi:[0,1]
	v_pk_fma_f32 v[180:181], v[220:221], v[220:221], v[180:181]
	v_pk_add_f32 v[218:219], v[56:57], v[236:237] op_sel_hi:[1,0] neg_lo:[0,1] neg_hi:[0,1]
	v_pk_fma_f32 v[182:183], v[218:219], v[218:219], v[182:183]
	v_pk_add_f32 v[220:221], v[64:65], v[150:151] op_sel_hi:[1,0] neg_lo:[0,1] neg_hi:[0,1]
	v_pk_fma_f32 v[184:185], v[220:221], v[220:221], v[184:185]
	v_pk_add_f32 v[218:219], v[66:67], v[132:133] op_sel_hi:[1,0] neg_lo:[0,1] neg_hi:[0,1]
	v_pk_fma_f32 v[170:171], v[218:219], v[218:219], v[170:171]
	v_pk_add_f32 v[220:221], v[74:75], v[134:135] op_sel_hi:[1,0] neg_lo:[0,1] neg_hi:[0,1]
	v_pk_fma_f32 v[172:173], v[220:221], v[220:221], v[172:173]
	v_pk_add_f32 v[218:219], v[82:83], v[136:137] op_sel_hi:[1,0] neg_lo:[0,1] neg_hi:[0,1]
	v_pk_fma_f32 v[174:175], v[218:219], v[218:219], v[174:175]
	v_pk_add_f32 v[220:221], v[90:91], v[138:139] op_sel_hi:[1,0] neg_lo:[0,1] neg_hi:[0,1]
	v_pk_fma_f32 v[176:177], v[220:221], v[220:221], v[176:177]
	v_pk_add_f32 v[218:219], v[2:3], v[232:233] op_sel_hi:[1,0] neg_lo:[0,1] neg_hi:[0,1]
	v_pk_fma_f32 v[178:179], v[218:219], v[218:219], v[178:179]
	v_pk_add_f32 v[220:221], v[10:11], v[234:235] op_sel_hi:[1,0] neg_lo:[0,1] neg_hi:[0,1]
	v_pk_fma_f32 v[180:181], v[220:221], v[220:221], v[180:181]
	v_pk_add_f32 v[218:219], v[18:19], v[236:237] op_sel_hi:[1,0] neg_lo:[0,1] neg_hi:[0,1]
	v_pk_fma_f32 v[182:183], v[218:219], v[218:219], v[182:183]
	v_pk_add_f32 v[220:221], v[26:27], v[150:151] op_sel_hi:[1,0] neg_lo:[0,1] neg_hi:[0,1]
	v_pk_fma_f32 v[184:185], v[220:221], v[220:221], v[184:185]
	v_pk_add_f32 v[218:219], v[68:69], v[132:133] op_sel_hi:[1,0] neg_lo:[0,1] neg_hi:[0,1]
	v_pk_fma_f32 v[170:171], v[218:219], v[218:219], v[170:171]
	v_pk_add_f32 v[220:221], v[76:77], v[134:135] op_sel_hi:[1,0] neg_lo:[0,1] neg_hi:[0,1]
	v_pk_fma_f32 v[172:173], v[220:221], v[220:221], v[172:173]
	v_pk_add_f32 v[218:219], v[84:85], v[136:137] op_sel_hi:[1,0] neg_lo:[0,1] neg_hi:[0,1]
	v_pk_fma_f32 v[174:175], v[218:219], v[218:219], v[174:175]
	v_pk_add_f32 v[220:221], v[92:93], v[138:139] op_sel_hi:[1,0] neg_lo:[0,1] neg_hi:[0,1]
	v_pk_fma_f32 v[176:177], v[220:221], v[220:221], v[176:177]
	v_pk_add_f32 v[218:219], v[4:5], v[232:233] op_sel_hi:[1,0] neg_lo:[0,1] neg_hi:[0,1]
	v_pk_fma_f32 v[178:179], v[218:219], v[218:219], v[178:179]
	v_pk_add_f32 v[220:221], v[12:13], v[234:235] op_sel_hi:[1,0] neg_lo:[0,1] neg_hi:[0,1]
	v_pk_fma_f32 v[180:181], v[220:221], v[220:221], v[180:181]
	v_pk_add_f32 v[218:219], v[20:21], v[236:237] op_sel_hi:[1,0] neg_lo:[0,1] neg_hi:[0,1]
	v_pk_fma_f32 v[182:183], v[218:219], v[218:219], v[182:183]
	v_pk_add_f32 v[220:221], v[28:29], v[150:151] op_sel_hi:[1,0] neg_lo:[0,1] neg_hi:[0,1]
	v_pk_fma_f32 v[184:185], v[220:221], v[220:221], v[184:185]
	v_pk_add_f32 v[218:219], v[70:71], v[132:133] op_sel_hi:[1,0] neg_lo:[0,1] neg_hi:[0,1]
	v_pk_fma_f32 v[170:171], v[218:219], v[218:219], v[170:171]
	v_pk_add_f32 v[220:221], v[78:79], v[134:135] op_sel_hi:[1,0] neg_lo:[0,1] neg_hi:[0,1]
	v_pk_fma_f32 v[172:173], v[220:221], v[220:221], v[172:173]
	v_pk_add_f32 v[218:219], v[86:87], v[136:137] op_sel_hi:[1,0] neg_lo:[0,1] neg_hi:[0,1]
	v_pk_fma_f32 v[174:175], v[218:219], v[218:219], v[174:175]
	v_pk_add_f32 v[220:221], v[94:95], v[138:139] op_sel_hi:[1,0] neg_lo:[0,1] neg_hi:[0,1]
	v_pk_fma_f32 v[176:177], v[220:221], v[220:221], v[176:177]
	v_pk_add_f32 v[218:219], v[6:7], v[232:233] op_sel_hi:[1,0] neg_lo:[0,1] neg_hi:[0,1]
	v_pk_fma_f32 v[178:179], v[218:219], v[218:219], v[178:179]
	v_pk_add_f32 v[220:221], v[14:15], v[234:235] op_sel_hi:[1,0] neg_lo:[0,1] neg_hi:[0,1]
	v_pk_fma_f32 v[180:181], v[220:221], v[220:221], v[180:181]
	v_pk_add_f32 v[218:219], v[22:23], v[236:237] op_sel_hi:[1,0] neg_lo:[0,1] neg_hi:[0,1]
	v_pk_fma_f32 v[182:183], v[218:219], v[218:219], v[182:183]
	v_pk_add_f32 v[220:221], v[30:31], v[150:151] op_sel_hi:[1,0] neg_lo:[0,1] neg_hi:[0,1]
	v_pk_fma_f32 v[184:185], v[220:221], v[220:221], v[184:185]
	v_pk_add_f32 v[218:219], v[72:73], v[132:133] op_sel_hi:[1,0] neg_lo:[0,1] neg_hi:[0,1]
	v_pk_fma_f32 v[170:171], v[218:219], v[218:219], v[170:171]
	v_pk_add_f32 v[220:221], v[80:81], v[134:135] op_sel_hi:[1,0] neg_lo:[0,1] neg_hi:[0,1]
	v_pk_fma_f32 v[172:173], v[220:221], v[220:221], v[172:173]
	v_pk_add_f32 v[218:219], v[88:89], v[136:137] op_sel_hi:[1,0] neg_lo:[0,1] neg_hi:[0,1]
	v_pk_fma_f32 v[174:175], v[218:219], v[218:219], v[174:175]
	v_pk_add_f32 v[220:221], v[96:97], v[138:139] op_sel_hi:[1,0] neg_lo:[0,1] neg_hi:[0,1]
	v_pk_fma_f32 v[176:177], v[220:221], v[220:221], v[176:177]
	v_pk_add_f32 v[218:219], v[8:9], v[232:233] op_sel_hi:[1,0] neg_lo:[0,1] neg_hi:[0,1]
	v_pk_fma_f32 v[178:179], v[218:219], v[218:219], v[178:179]
	v_pk_add_f32 v[220:221], v[16:17], v[234:235] op_sel_hi:[1,0] neg_lo:[0,1] neg_hi:[0,1]
	v_pk_fma_f32 v[180:181], v[220:221], v[220:221], v[180:181]
	v_pk_add_f32 v[218:219], v[24:25], v[236:237] op_sel_hi:[1,0] neg_lo:[0,1] neg_hi:[0,1]
	v_pk_fma_f32 v[182:183], v[218:219], v[218:219], v[182:183]
	v_pk_add_f32 v[220:221], v[32:33], v[150:151] op_sel_hi:[1,0] neg_lo:[0,1] neg_hi:[0,1]
	v_pk_fma_f32 v[184:185], v[220:221], v[220:221], v[184:185]
	v_add_f32_e32 v133, v170, v171
	v_add_f32_e32 v135, v172, v173
	v_add_f32_e32 v137, v174, v175
	v_add_f32_e32 v139, v176, v177
	v_add_f32_e32 v233, v178, v179
	v_add_f32_e32 v235, v180, v181
	v_add_f32_e32 v237, v182, v183
	v_add_f32_e32 v151, v184, v185
	v_add_f32_dpp v133, v133, v133 quad_perm:[1,0,3,2] row_mask:0xf bank_mask:0xf
	v_add_f32_dpp v135, v135, v135 quad_perm:[1,0,3,2] row_mask:0xf bank_mask:0xf
	v_add_f32_dpp v137, v137, v137 quad_perm:[1,0,3,2] row_mask:0xf bank_mask:0xf
	v_add_f32_dpp v139, v139, v139 quad_perm:[1,0,3,2] row_mask:0xf bank_mask:0xf
	v_add_f32_dpp v233, v233, v233 quad_perm:[1,0,3,2] row_mask:0xf bank_mask:0xf
	v_add_f32_dpp v235, v235, v235 quad_perm:[1,0,3,2] row_mask:0xf bank_mask:0xf
	v_add_f32_dpp v237, v237, v237 quad_perm:[1,0,3,2] row_mask:0xf bank_mask:0xf
	v_add_f32_dpp v151, v151, v151 quad_perm:[1,0,3,2] row_mask:0xf bank_mask:0xf
	v_add_f32_dpp v133, v133, v133 quad_perm:[2,3,0,1] row_mask:0xf bank_mask:0xf
	v_add_f32_dpp v135, v135, v135 quad_perm:[2,3,0,1] row_mask:0xf bank_mask:0xf
	v_add_f32_dpp v137, v137, v137 quad_perm:[2,3,0,1] row_mask:0xf bank_mask:0xf
	v_add_f32_dpp v139, v139, v139 quad_perm:[2,3,0,1] row_mask:0xf bank_mask:0xf
	v_add_f32_dpp v233, v233, v233 quad_perm:[2,3,0,1] row_mask:0xf bank_mask:0xf
	v_add_f32_dpp v235, v235, v235 quad_perm:[2,3,0,1] row_mask:0xf bank_mask:0xf
	v_add_f32_dpp v237, v237, v237 quad_perm:[2,3,0,1] row_mask:0xf bank_mask:0xf
	v_add_f32_dpp v151, v151, v151 quad_perm:[2,3,0,1] row_mask:0xf bank_mask:0xf
	v_add_f32_dpp v133, v133, v133 row_half_mirror row_mask:0xf bank_mask:0xf
	v_add_f32_dpp v135, v135, v135 row_half_mirror row_mask:0xf bank_mask:0xf
	v_add_f32_dpp v137, v137, v137 row_half_mirror row_mask:0xf bank_mask:0xf
	v_add_f32_dpp v139, v139, v139 row_half_mirror row_mask:0xf bank_mask:0xf
	v_add_f32_dpp v233, v233, v233 row_half_mirror row_mask:0xf bank_mask:0xf
	v_add_f32_dpp v235, v235, v235 row_half_mirror row_mask:0xf bank_mask:0xf
	v_add_f32_dpp v237, v237, v237 row_half_mirror row_mask:0xf bank_mask:0xf
	v_add_f32_dpp v151, v151, v151 row_half_mirror row_mask:0xf bank_mask:0xf
	v_add_f32_dpp v133, v133, v133 row_mirror row_mask:0xf bank_mask:0xf
	v_add_f32_dpp v135, v135, v135 row_mirror row_mask:0xf bank_mask:0xf
	v_add_f32_dpp v137, v137, v137 row_mirror row_mask:0xf bank_mask:0xf
	v_add_f32_dpp v139, v139, v139 row_mirror row_mask:0xf bank_mask:0xf
	v_add_f32_dpp v233, v233, v233 row_mirror row_mask:0xf bank_mask:0xf
	v_add_f32_dpp v235, v235, v235 row_mirror row_mask:0xf bank_mask:0xf
	v_add_f32_dpp v237, v237, v237 row_mirror row_mask:0xf bank_mask:0xf
	v_add_f32_dpp v151, v151, v151 row_mirror row_mask:0xf bank_mask:0xf
	s_lshr_b32 s0, s73, 8
	s_lshl_b32 s0, s0, 13
	s_add_u32 s40, s62, 0xf100000
	s_addc_u32 s41, s63, 0
	s_add_u32 s40, s40, s0
	s_addc_u32 s41, s41, 0
	s_lshr_b32 s0, s46, 8
	s_lshl_b32 s0, s0, 11
	v_add_u32_e32 v224, s0, v227
	s_mov_b32 exec_lo, 0x10001
	s_mov_b32 exec_hi, 0x10001
	global_store_dwordx2 v224, v[132:133], s[40:41] offset:0 sc1
	global_store_dwordx2 v224, v[134:135], s[40:41] offset:256 sc1
	global_store_dwordx2 v224, v[136:137], s[40:41] offset:512 sc1
	global_store_dwordx2 v224, v[138:139], s[40:41] offset:768 sc1
	global_store_dwordx2 v224, v[232:233], s[40:41] offset:1024 sc1
	global_store_dwordx2 v224, v[234:235], s[40:41] offset:1280 sc1
	global_store_dwordx2 v224, v[236:237], s[40:41] offset:1536 sc1
	global_store_dwordx2 v224, v[150:151], s[40:41] offset:1792 sc1
	s_mov_b64 exec, -1
	s_waitcnt vmcnt(0)
	s_barrier
	v_readfirstlane_b32 s98, v0
	s_nop 3
	s_lshr_b32 s98, s98, 6
	s_cmp_lg_u32 s98, 0
	s_cbranch_scc0 .Lp9_signal
	s_mov_b32 s38, 0x0
	s_mov_b32 s39, 0
	v_lshl_add_u64 v[154:155], v[230:231], 0, s[38:39]
	global_store_dwordx4 v[154:155], v[98:101], off
	global_store_dwordx4 v[154:155], v[102:105], off offset:16
	s_mov_b32 s38, 0x20000
	s_mov_b32 s39, 0
	v_lshl_add_u64 v[156:157], v[230:231], 0, s[38:39]
	global_store_dwordx4 v[156:157], v[106:109], off
	global_store_dwordx4 v[156:157], v[110:113], off offset:16
	s_mov_b32 s38, 0x40000
	s_mov_b32 s39, 0
	v_lshl_add_u64 v[154:155], v[230:231], 0, s[38:39]
	global_store_dwordx4 v[154:155], v[114:117], off
	global_store_dwordx4 v[154:155], v[118:121], off offset:16
	s_mov_b32 s38, 0x60000
	s_mov_b32 s39, 0
	v_lshl_add_u64 v[156:157], v[230:231], 0, s[38:39]
	global_store_dwordx4 v[156:157], v[122:125], off
	global_store_dwordx4 v[156:157], v[126:129], off offset:16
	s_mov_b32 s38, 0x200
	s_mov_b32 s39, 0
	v_lshl_add_u64 v[154:155], v[230:231], 0, s[38:39]
	global_store_dwordx4 v[154:155], v[66:69], off
	global_store_dwordx4 v[154:155], v[70:73], off offset:16
	s_mov_b32 s38, 0x20200
	s_mov_b32 s39, 0
	v_lshl_add_u64 v[156:157], v[230:231], 0, s[38:39]
	global_store_dwordx4 v[156:157], v[74:77], off
	global_store_dwordx4 v[156:157], v[78:81], off offset:16
	s_mov_b32 s38, 0x40200
	s_mov_b32 s39, 0
	v_lshl_add_u64 v[154:155], v[230:231], 0, s[38:39]
	global_store_dwordx4 v[154:155], v[82:85], off
	global_store_dwordx4 v[154:155], v[86:89], off offset:16
	s_mov_b32 s38, 0x60200
	s_mov_b32 s39, 0
	v_lshl_add_u64 v[156:157], v[230:231], 0, s[38:39]
	global_store_dwordx4 v[156:157], v[90:93], off
	global_store_dwordx4 v[156:157], v[94:97], off offset:16
	s_branch .Lp9_wait_done

.Lp9_wait_done:
	s_barrier
	v_and_b32_e32 v246, 7, v0
	v_lshrrev_b32_e32 v247, 2, v246
	v_and_b32_e32 v246, 3, v246
	v_lshlrev_b32_e32 v247, 10, v247
	v_lshl_add_u32 v246, v246, 8, v247
	v_add_u32_e32 v246, v246, v227
	v_add_u32_e32 v247, 0x1000, v246
	global_load_dwordx2 v[238:239], v246, s[40:41] sc1
	global_load_dwordx2 v[240:241], v246, s[40:41] offset:2048 sc1
	global_load_dwordx2 v[242:243], v247, s[40:41] sc1
	global_load_dwordx2 v[244:245], v247, s[40:41] offset:2048 sc1
	v_readfirstlane_b32 s98, v0
	s_nop 3
	s_lshr_b32 s98, s98, 6
	s_cmp_lg_u32 s98, 0
	s_cbranch_scc1 .Lp9_w0done
	s_mov_b32 s38, 0x0
	s_mov_b32 s39, 0
	v_lshl_add_u64 v[154:155], v[230:231], 0, s[38:39]
	global_store_dwordx4 v[154:155], v[98:101], off
	global_store_dwordx4 v[154:155], v[102:105], off offset:16
	s_mov_b32 s38, 0x20000
	s_mov_b32 s39, 0
	v_lshl_add_u64 v[156:157], v[230:231], 0, s[38:39]
	global_store_dwordx4 v[156:157], v[106:109], off
	global_store_dwordx4 v[156:157], v[110:113], off offset:16
	s_mov_b32 s38, 0x40000
	s_mov_b32 s39, 0
	v_lshl_add_u64 v[154:155], v[230:231], 0, s[38:39]
	global_store_dwordx4 v[154:155], v[114:117], off
	global_store_dwordx4 v[154:155], v[118:121], off offset:16
	s_mov_b32 s38, 0x60000
	s_mov_b32 s39, 0
	v_lshl_add_u64 v[156:157], v[230:231], 0, s[38:39]
	global_store_dwordx4 v[156:157], v[122:125], off
	global_store_dwordx4 v[156:157], v[126:129], off offset:16
	s_mov_b32 s38, 0x200
	s_mov_b32 s39, 0
	v_lshl_add_u64 v[154:155], v[230:231], 0, s[38:39]
	global_store_dwordx4 v[154:155], v[66:69], off
	global_store_dwordx4 v[154:155], v[70:73], off offset:16
	s_mov_b32 s38, 0x20200
	s_mov_b32 s39, 0
	v_lshl_add_u64 v[156:157], v[230:231], 0, s[38:39]
	global_store_dwordx4 v[156:157], v[74:77], off
	global_store_dwordx4 v[156:157], v[78:81], off offset:16
	s_mov_b32 s38, 0x40200
	s_mov_b32 s39, 0
	v_lshl_add_u64 v[154:155], v[230:231], 0, s[38:39]
	global_store_dwordx4 v[154:155], v[82:85], off
	global_store_dwordx4 v[154:155], v[86:89], off offset:16
	s_mov_b32 s38, 0x60200
	s_mov_b32 s39, 0
	v_lshl_add_u64 v[156:157], v[230:231], 0, s[38:39]
	global_store_dwordx4 v[156:157], v[90:93], off
	global_store_dwordx4 v[156:157], v[94:97], off offset:16
	s_mov_b32 s38, 0x80000
	s_mov_b32 s39, 0
	v_lshl_add_u64 v[154:155], v[230:231], 0, s[38:39]
	global_store_dwordx4 v[154:155], v[34:37], off
	global_store_dwordx4 v[154:155], v[38:41], off offset:16
	s_mov_b32 s38, 0xa0000
	s_mov_b32 s39, 0
	v_lshl_add_u64 v[156:157], v[230:231], 0, s[38:39]
	global_store_dwordx4 v[156:157], v[42:45], off
	global_store_dwordx4 v[156:157], v[46:49], off offset:16
	s_mov_b32 s38, 0xc0000
	s_mov_b32 s39, 0
	v_lshl_add_u64 v[154:155], v[230:231], 0, s[38:39]
	global_store_dwordx4 v[154:155], v[50:53], off
	global_store_dwordx4 v[154:155], v[54:57], off offset:16
	s_mov_b32 s38, 0xe0000
	s_mov_b32 s39, 0
	v_lshl_add_u64 v[156:157], v[230:231], 0, s[38:39]
	global_store_dwordx4 v[156:157], v[58:61], off
	global_store_dwordx4 v[156:157], v[62:65], off offset:16
	s_mov_b32 s38, 0x80200
	s_mov_b32 s39, 0
	v_lshl_add_u64 v[154:155], v[230:231], 0, s[38:39]
	global_store_dwordx4 v[154:155], v[2:5], off
	global_store_dwordx4 v[154:155], v[6:9], off offset:16
	s_mov_b32 s38, 0xa0200
	s_mov_b32 s39, 0
	v_lshl_add_u64 v[156:157], v[230:231], 0, s[38:39]
	global_store_dwordx4 v[156:157], v[10:13], off
	global_store_dwordx4 v[156:157], v[14:17], off offset:16
	s_mov_b32 s38, 0xc0200
	s_mov_b32 s39, 0
	v_lshl_add_u64 v[154:155], v[230:231], 0, s[38:39]
	global_store_dwordx4 v[154:155], v[18:21], off
	global_store_dwordx4 v[154:155], v[22:25], off offset:16
	s_mov_b32 s38, 0xe0200
	s_mov_b32 s39, 0
	v_lshl_add_u64 v[156:157], v[230:231], 0, s[38:39]
	global_store_dwordx4 v[156:157], v[26:29], off
	global_store_dwordx4 v[156:157], v[30:33], off offset:16
	s_waitcnt vmcnt(32)
	s_branch .Lp9_comb
.Lp9_w0done:
	s_mov_b32 s38, 0x80000
	s_mov_b32 s39, 0
	v_lshl_add_u64 v[154:155], v[230:231], 0, s[38:39]
	global_store_dwordx4 v[154:155], v[34:37], off
	global_store_dwordx4 v[154:155], v[38:41], off offset:16
	s_mov_b32 s38, 0xa0000
	s_mov_b32 s39, 0
	v_lshl_add_u64 v[156:157], v[230:231], 0, s[38:39]
	global_store_dwordx4 v[156:157], v[42:45], off
	global_store_dwordx4 v[156:157], v[46:49], off offset:16
	s_mov_b32 s38, 0xc0000
	s_mov_b32 s39, 0
	v_lshl_add_u64 v[154:155], v[230:231], 0, s[38:39]
	global_store_dwordx4 v[154:155], v[50:53], off
	global_store_dwordx4 v[154:155], v[54:57], off offset:16
	s_mov_b32 s38, 0xe0000
	s_mov_b32 s39, 0
	v_lshl_add_u64 v[156:157], v[230:231], 0, s[38:39]
	global_store_dwordx4 v[156:157], v[58:61], off
	global_store_dwordx4 v[156:157], v[62:65], off offset:16
	s_mov_b32 s38, 0x80200
	s_mov_b32 s39, 0
	v_lshl_add_u64 v[154:155], v[230:231], 0, s[38:39]
	global_store_dwordx4 v[154:155], v[2:5], off
	global_store_dwordx4 v[154:155], v[6:9], off offset:16
	s_mov_b32 s38, 0xa0200
	s_mov_b32 s39, 0
	v_lshl_add_u64 v[156:157], v[230:231], 0, s[38:39]
	global_store_dwordx4 v[156:157], v[10:13], off
	global_store_dwordx4 v[156:157], v[14:17], off offset:16
	s_mov_b32 s38, 0xc0200
	s_mov_b32 s39, 0
	v_lshl_add_u64 v[154:155], v[230:231], 0, s[38:39]
	global_store_dwordx4 v[154:155], v[18:21], off
	global_store_dwordx4 v[154:155], v[22:25], off offset:16
	s_mov_b32 s38, 0xe0200
	s_mov_b32 s39, 0
	v_lshl_add_u64 v[156:157], v[230:231], 0, s[38:39]
	global_store_dwordx4 v[156:157], v[26:29], off
	global_store_dwordx4 v[156:157], v[30:33], off offset:16
	s_waitcnt vmcnt(16)
.Lp9_comb:
	v_mov_b32_e32 v248, 0x3727c5ac
	v_and_b32_e32 v249, 48, v0
	v_lshlrev_b32_e32 v249, 2, v249
	v_add_f32_e32 v250, v238, v240
	v_add_f32_e32 v246, v242, v244
	v_add_f32_e32 v250, v250, v246
	v_mul_f32_e32 v250, 0x3e800000, v250
	v_sub_f32_e32 v238, v238, v250
	v_sub_f32_e32 v240, v240, v250
	v_sub_f32_e32 v242, v242, v250
	v_sub_f32_e32 v244, v244, v250
	v_mul_f32_e32 v246, v238, v238
	v_fmac_f32_e32 v246, v240, v240
	v_fmac_f32_e32 v246, v242, v242
	v_fmac_f32_e32 v246, v244, v244
	v_add_f32_e32 v239, v239, v241
	v_add_f32_e32 v243, v243, v245
	v_add_f32_e32 v239, v239, v243
	v_fmamk_f32 v246, v246, 0x43800000, v239
	v_fmamk_f32 v246, v246, 0x3a800000, v248
	v_rsq_f32_e32 v251, v246
	s_nop 0
	v_add_u32_e32 v240, 0, v249
	ds_bpermute_b32 v132, v240, v250
	ds_bpermute_b32 v133, v240, v251
	v_add_u32_e32 v241, 4, v249
	ds_bpermute_b32 v134, v241, v250
	ds_bpermute_b32 v135, v241, v251
	v_add_u32_e32 v240, 8, v249
	ds_bpermute_b32 v136, v240, v250
	ds_bpermute_b32 v137, v240, v251
	v_add_u32_e32 v241, 12, v249
	ds_bpermute_b32 v138, v241, v250
	ds_bpermute_b32 v139, v241, v251
	v_add_u32_e32 v240, 16, v249
	ds_bpermute_b32 v232, v240, v250
	ds_bpermute_b32 v233, v240, v251
	v_add_u32_e32 v241, 20, v249
	ds_bpermute_b32 v234, v241, v250
	ds_bpermute_b32 v235, v241, v251
	v_add_u32_e32 v240, 24, v249
	ds_bpermute_b32 v236, v240, v250
	ds_bpermute_b32 v237, v240, v251
	v_add_u32_e32 v241, 28, v249
	ds_bpermute_b32 v150, v241, v250
	ds_bpermute_b32 v151, v241, v251
	s_waitcnt lgkmcnt(0)
	s_lshr_b32 s0, s46, 8
	s_cmp_lg_u32 s0, 0
	s_cbranch_scc1 .Lp9_nostats
	s_mov_b32 exec_lo, 0x10001
	s_mov_b32 exec_hi, 0x10001
	global_store_dwordx2 v227, v[132:133], s[52:53] offset:0
	global_store_dwordx2 v227, v[134:135], s[52:53] offset:256
	global_store_dwordx2 v227, v[136:137], s[52:53] offset:512
	global_store_dwordx2 v227, v[138:139], s[52:53] offset:768
	global_store_dwordx2 v227, v[232:233], s[52:53] offset:1024
	global_store_dwordx2 v227, v[234:235], s[52:53] offset:1280
	global_store_dwordx2 v227, v[236:237], s[52:53] offset:1536
	global_store_dwordx2 v227, v[150:151], s[52:53] offset:1792
	s_mov_b64 exec, -1

.LBB0_1595:
	v_add_u32_e32 v2, s1, v168
	v_ashrrev_i32_e32 v3, 31, v2
	v_add_u32_e32 v4, 16, v2
	v_lshlrev_b64 v[2:3], 11, v[2:3]
	v_ashrrev_i32_e32 v5, 31, v4
	v_lshl_add_u64 v[2:3], v[156:157], 0, v[2:3]
	v_lshlrev_b64 v[6:7], 11, v[4:5]
	global_load_dwordx4 v[2:5], v[2:3], off
	v_lshl_add_u64 v[6:7], v[156:157], 0, v[6:7]
	global_load_dwordx4 v[114:117], v[6:7], off
	s_add_i32 s1, s1, 32
	s_cmpk_eq_i32 s1, 0x80
	s_waitcnt vmcnt(1)
	v_mfma_f32_32x32x16_bf16 v[176:191], v[2:5], v[130:133], 0
	v_mfma_f32_32x32x16_bf16 v[192:207], v[2:5], v[134:137], 0
	v_mfma_f32_32x32x16_bf16 v[208:223], v[2:5], v[138:141], 0
	v_mfma_f32_32x32x16_bf16 v[224:239], v[2:5], v[142:145], 0
	s_waitcnt vmcnt(0)
	v_mfma_f32_32x32x16_bf16 v[50:65], v[114:117], v[130:133], 0
	v_mfma_f32_32x32x16_bf16 v[66:81], v[114:117], v[134:137], 0
	v_mfma_f32_32x32x16_bf16 v[82:97], v[114:117], v[138:141], 0
	v_mfma_f32_32x32x16_bf16 v[98:113], v[114:117], v[142:145], 0
	s_nop 7
	v_fma_f32 v244, -v153, v35, v176
	v_fma_f32 v245, v153, v34, v192
	v_fma_f32 v246, -v155, v119, v208
	v_fma_f32 v247, v155, v118, v224
	v_fma_f32 v240, v152, v34, v244
	v_fma_f32 v241, v152, v35, v245
	v_fma_f32 v242, v154, v118, v246
	v_fma_f32 v243, v154, v119, v247
	v_fma_f32 v244, -v153, v241, v177
	v_fma_f32 v245, v153, v240, v193
	v_fma_f32 v246, -v155, v243, v209
	v_fma_f32 v247, v155, v242, v225
	v_fma_f32 v34, v152, v240, v244
	v_fma_f32 v35, v152, v241, v245
	v_fma_f32 v118, v154, v242, v246
	v_fma_f32 v119, v154, v243, v247
	v_fma_f32 v244, -v153, v35, v178
	v_fma_f32 v245, v153, v34, v194
	v_fma_f32 v246, -v155, v119, v210
	v_fma_f32 v247, v155, v118, v226
	v_fma_f32 v240, v152, v34, v244
	v_fma_f32 v241, v152, v35, v245
	v_fma_f32 v242, v154, v118, v246
	v_fma_f32 v243, v154, v119, v247
	v_fma_f32 v244, -v153, v241, v179
	v_fma_f32 v245, v153, v240, v195
	v_fma_f32 v246, -v155, v243, v211
	v_fma_f32 v247, v155, v242, v227
	v_fma_f32 v34, v152, v240, v244
	v_fma_f32 v35, v152, v241, v245
	v_fma_f32 v118, v154, v242, v246
	v_fma_f32 v119, v154, v243, v247
	v_fma_f32 v244, -v153, v35, v180
	v_fma_f32 v245, v153, v34, v196
	v_fma_f32 v246, -v155, v119, v212
	v_fma_f32 v247, v155, v118, v228
	v_fma_f32 v240, v152, v34, v244
	v_fma_f32 v241, v152, v35, v245
	v_fma_f32 v242, v154, v118, v246
	v_fma_f32 v243, v154, v119, v247
	v_fma_f32 v244, -v153, v241, v181
	v_fma_f32 v245, v153, v240, v197
	v_fma_f32 v246, -v155, v243, v213
	v_fma_f32 v247, v155, v242, v229
	v_fma_f32 v34, v152, v240, v244
	v_fma_f32 v35, v152, v241, v245
	v_fma_f32 v118, v154, v242, v246
	v_fma_f32 v119, v154, v243, v247
	v_fma_f32 v244, -v153, v35, v182
	v_fma_f32 v245, v153, v34, v198
	v_fma_f32 v246, -v155, v119, v214
	v_fma_f32 v247, v155, v118, v230
	v_fma_f32 v240, v152, v34, v244
	v_fma_f32 v241, v152, v35, v245
	v_fma_f32 v242, v154, v118, v246
	v_fma_f32 v243, v154, v119, v247
	v_fma_f32 v244, -v153, v241, v183
	v_fma_f32 v245, v153, v240, v199
	v_fma_f32 v246, -v155, v243, v215
	v_fma_f32 v247, v155, v242, v231
	v_fma_f32 v34, v152, v240, v244
	v_fma_f32 v35, v152, v241, v245
	v_fma_f32 v118, v154, v242, v246
	v_fma_f32 v119, v154, v243, v247
	v_fma_f32 v244, -v153, v35, v184
	v_fma_f32 v245, v153, v34, v200
	v_fma_f32 v246, -v155, v119, v216
	v_fma_f32 v247, v155, v118, v232
	v_fma_f32 v240, v152, v34, v244
	v_fma_f32 v241, v152, v35, v245
	v_fma_f32 v242, v154, v118, v246
	v_fma_f32 v243, v154, v119, v247
	v_fma_f32 v244, -v153, v241, v185
	v_fma_f32 v245, v153, v240, v201
	v_fma_f32 v246, -v155, v243, v217
	v_fma_f32 v247, v155, v242, v233
	v_fma_f32 v34, v152, v240, v244
	v_fma_f32 v35, v152, v241, v245
	v_fma_f32 v118, v154, v242, v246
	v_fma_f32 v119, v154, v243, v247
	v_fma_f32 v244, -v153, v35, v186
	v_fma_f32 v245, v153, v34, v202
	v_fma_f32 v246, -v155, v119, v218
	v_fma_f32 v247, v155, v118, v234
	v_fma_f32 v240, v152, v34, v244
	v_fma_f32 v241, v152, v35, v245
	v_fma_f32 v242, v154, v118, v246
	v_fma_f32 v243, v154, v119, v247
	v_fma_f32 v244, -v153, v241, v187
	v_fma_f32 v245, v153, v240, v203
	v_fma_f32 v246, -v155, v243, v219
	v_fma_f32 v247, v155, v242, v235
	v_fma_f32 v34, v152, v240, v244
	v_fma_f32 v35, v152, v241, v245
	v_fma_f32 v118, v154, v242, v246
	v_fma_f32 v119, v154, v243, v247
	v_fma_f32 v244, -v153, v35, v188
	v_fma_f32 v245, v153, v34, v204
	v_fma_f32 v246, -v155, v119, v220
	v_fma_f32 v247, v155, v118, v236
	v_fma_f32 v240, v152, v34, v244
	v_fma_f32 v241, v152, v35, v245
	v_fma_f32 v242, v154, v118, v246
	v_fma_f32 v243, v154, v119, v247
	v_fma_f32 v244, -v153, v241, v189
	v_fma_f32 v245, v153, v240, v205
	v_fma_f32 v246, -v155, v243, v221
	v_fma_f32 v247, v155, v242, v237
	v_fma_f32 v34, v152, v240, v244
	v_fma_f32 v35, v152, v241, v245
	v_fma_f32 v118, v154, v242, v246
	v_fma_f32 v119, v154, v243, v247
	v_fma_f32 v244, -v153, v35, v190
	v_fma_f32 v245, v153, v34, v206
	v_fma_f32 v246, -v155, v119, v222
	v_fma_f32 v247, v155, v118, v238
	v_fma_f32 v240, v152, v34, v244
	v_fma_f32 v241, v152, v35, v245
	v_fma_f32 v242, v154, v118, v246
	v_fma_f32 v243, v154, v119, v247
	v_fma_f32 v244, -v153, v241, v191
	v_fma_f32 v245, v153, v240, v207
	v_fma_f32 v246, -v155, v243, v223
	v_fma_f32 v247, v155, v242, v239
	v_fma_f32 v34, v152, v240, v244
	v_fma_f32 v35, v152, v241, v245
	v_fma_f32 v118, v154, v242, v246
	v_fma_f32 v119, v154, v243, v247
	v_fma_f32 v244, -v153, v35, v50
	v_fma_f32 v245, v153, v34, v66
	v_fma_f32 v246, -v155, v119, v82
	v_fma_f32 v247, v155, v118, v98
	v_fma_f32 v240, v152, v34, v244
	v_fma_f32 v241, v152, v35, v245
	v_fma_f32 v242, v154, v118, v246
	v_fma_f32 v243, v154, v119, v247
	v_fma_f32 v244, -v153, v241, v51
	v_fma_f32 v245, v153, v240, v67
	v_fma_f32 v246, -v155, v243, v83
	v_fma_f32 v247, v155, v242, v99
	v_fma_f32 v34, v152, v240, v244
	v_fma_f32 v35, v152, v241, v245
	v_fma_f32 v118, v154, v242, v246
	v_fma_f32 v119, v154, v243, v247
	v_fma_f32 v244, -v153, v35, v52
	v_fma_f32 v245, v153, v34, v68
	v_fma_f32 v246, -v155, v119, v84
	v_fma_f32 v247, v155, v118, v100
	v_fma_f32 v240, v152, v34, v244
	v_fma_f32 v241, v152, v35, v245
	v_fma_f32 v242, v154, v118, v246
	v_fma_f32 v243, v154, v119, v247
	v_fma_f32 v244, -v153, v241, v53
	v_fma_f32 v245, v153, v240, v69
	v_fma_f32 v246, -v155, v243, v85
	v_fma_f32 v247, v155, v242, v101
	v_fma_f32 v34, v152, v240, v244
	v_fma_f32 v35, v152, v241, v245
	v_fma_f32 v118, v154, v242, v246
	v_fma_f32 v119, v154, v243, v247
	v_fma_f32 v244, -v153, v35, v54
	v_fma_f32 v245, v153, v34, v70
	v_fma_f32 v246, -v155, v119, v86
	v_fma_f32 v247, v155, v118, v102
	v_fma_f32 v240, v152, v34, v244
	v_fma_f32 v241, v152, v35, v245
	v_fma_f32 v242, v154, v118, v246
	v_fma_f32 v243, v154, v119, v247
	v_fma_f32 v244, -v153, v241, v55
	v_fma_f32 v245, v153, v240, v71
	v_fma_f32 v246, -v155, v243, v87
	v_fma_f32 v247, v155, v242, v103
	v_fma_f32 v34, v152, v240, v244
	v_fma_f32 v35, v152, v241, v245
	v_fma_f32 v118, v154, v242, v246
	v_fma_f32 v119, v154, v243, v247
	v_fma_f32 v244, -v153, v35, v56
	v_fma_f32 v245, v153, v34, v72
	v_fma_f32 v246, -v155, v119, v88
	v_fma_f32 v247, v155, v118, v104
	v_fma_f32 v240, v152, v34, v244
	v_fma_f32 v241, v152, v35, v245
	v_fma_f32 v242, v154, v118, v246
	v_fma_f32 v243, v154, v119, v247
	v_fma_f32 v244, -v153, v241, v57
	v_fma_f32 v245, v153, v240, v73
	v_fma_f32 v246, -v155, v243, v89
	v_fma_f32 v247, v155, v242, v105
	v_fma_f32 v34, v152, v240, v244
	v_fma_f32 v35, v152, v241, v245
	v_fma_f32 v118, v154, v242, v246
	v_fma_f32 v119, v154, v243, v247
	v_fma_f32 v244, -v153, v35, v58
	v_fma_f32 v245, v153, v34, v74
	v_fma_f32 v246, -v155, v119, v90
	v_fma_f32 v247, v155, v118, v106
	v_fma_f32 v240, v152, v34, v244
	v_fma_f32 v241, v152, v35, v245
	v_fma_f32 v242, v154, v118, v246
	v_fma_f32 v243, v154, v119, v247
	v_fma_f32 v244, -v153, v241, v59
	v_fma_f32 v245, v153, v240, v75
	v_fma_f32 v246, -v155, v243, v91
	v_fma_f32 v247, v155, v242, v107
	v_fma_f32 v34, v152, v240, v244
	v_fma_f32 v35, v152, v241, v245
	v_fma_f32 v118, v154, v242, v246
	v_fma_f32 v119, v154, v243, v247
	v_fma_f32 v244, -v153, v35, v60
	v_fma_f32 v245, v153, v34, v76
	v_fma_f32 v246, -v155, v119, v92
	v_fma_f32 v247, v155, v118, v108
	v_fma_f32 v240, v152, v34, v244
	v_fma_f32 v241, v152, v35, v245
	v_fma_f32 v242, v154, v118, v246
	v_fma_f32 v243, v154, v119, v247
	v_fma_f32 v244, -v153, v241, v61
	v_fma_f32 v245, v153, v240, v77
	v_fma_f32 v246, -v155, v243, v93
	v_fma_f32 v247, v155, v242, v109
	v_fma_f32 v34, v152, v240, v244
	v_fma_f32 v35, v152, v241, v245
	v_fma_f32 v118, v154, v242, v246
	v_fma_f32 v119, v154, v243, v247
	v_fma_f32 v244, -v153, v35, v62
	v_fma_f32 v245, v153, v34, v78
	v_fma_f32 v246, -v155, v119, v94
	v_fma_f32 v247, v155, v118, v110
	v_fma_f32 v240, v152, v34, v244
	v_fma_f32 v241, v152, v35, v245
	v_fma_f32 v242, v154, v118, v246
	v_fma_f32 v243, v154, v119, v247
	v_fma_f32 v244, -v153, v241, v63
	v_fma_f32 v245, v153, v240, v79
	v_fma_f32 v246, -v155, v243, v95
	v_fma_f32 v247, v155, v242, v111
	v_fma_f32 v34, v152, v240, v244
	v_fma_f32 v35, v152, v241, v245
	v_fma_f32 v118, v154, v242, v246
	v_fma_f32 v119, v154, v243, v247
	v_fma_f32 v244, -v153, v35, v64
	v_fma_f32 v245, v153, v34, v80
	v_fma_f32 v246, -v155, v119, v96
	v_fma_f32 v247, v155, v118, v112
	v_fma_f32 v240, v152, v34, v244
	v_fma_f32 v241, v152, v35, v245
	v_fma_f32 v242, v154, v118, v246
	v_fma_f32 v243, v154, v119, v247
	v_fma_f32 v244, -v153, v241, v65
	v_fma_f32 v245, v153, v240, v81
	v_fma_f32 v246, -v155, v243, v97
	v_fma_f32 v247, v155, v242, v113
	v_fma_f32 v34, v152, v240, v244
	v_fma_f32 v35, v152, v241, v245
	v_fma_f32 v118, v154, v242, v246
	v_fma_f32 v119, v154, v243, v247
	s_cbranch_scc0 .LBB0_1595
	s_nop 0
	s_nop 0
	s_nop 0
	s_nop 0
	s_nop 0
	s_nop 0
	s_nop 0
	s_nop 0
	s_nop 0
	v_lshlrev_b32_e32 v2, 7, v167
	v_or3_b32 v2, v2, v163, v166
	v_ashrrev_i32_e32 v3, 31, v2
	v_lshlrev_b64 v[2:3], 9, v[2:3]
	s_add_i32 s0, s0, s96
	v_lshl_add_u64 v[2:3], v[150:151], 0, v[2:3]
	s_cmpk_gt_i32 s0, 0x1ff
	global_store_dwordx2 v[2:3], v[34:35], off
	global_store_dwordx2 v[2:3], v[118:119], off offset:256
	s_cbranch_scc0 .LBB0_1594
